# v91 + relaxed first K-loop iteration per unit (first two vmcnt(8) of the peeled iterations dropped, unit-start drains removed, prologue wait vmcnt(0))
# baseline (speedup 1.0000x reference)
; #define PG8_STAGE(bufoff, gbase, voff) do { _Pragma("unroll") for (int _i = 0; _i < 2; ++_i) \
;         __builtin_amdgcn_global_load_lds((const unsigned*)((const char*)(gbase) + (voff)[_i]), (PG8_LAS unsigned*)(lds + (bufoff) + ldsw + _i * 8192), 16, 0, 0); } while (0)
; #define PG8_LDA(dst, b, h) do { _Pragma("unroll") for (int m = 0; m < 4; ++m) _Pragma("unroll") for (int k = 0; k < 2; ++k) dst[m][k] = *(const PG8_LAS bf16x8*)(lds + PG8_SA(b, h) + aoff + m * 2048 + k * 1024); } while (0)
; #define PG8_LDB(dst, b, h) do { _Pragma("unroll") for (int n = 0; n < 2; ++n) _Pragma("unroll") for (int k = 0; k < 2; ++k) dst[n][k] = *(const PG8_LAS bf16x8*)(lds + PG8_SB(b, h) + boff + n * 2048 + k * 1024); } while (0)
; #define PG8_MMA(ai, bj, At, Bt) do { __builtin_amdgcn_s_setprio(1); _Pragma("unroll") for (int m = 0; m < 4; ++m) _Pragma("unroll") for (int n = 0; n < 2; ++n) _Pragma("unroll") for (int k = 0; k < 2; ++k) \
;         acc[ai][bj][m][n] = mma16<Epi::I8>(Bt[n][k], At[m][k], acc[ai][bj][m][n]); __builtin_amdgcn_s_setprio(0); } while (0)
; #define PG8_WAIT_V(n) asm volatile("s_waitcnt vmcnt(" #n ")" ::: "memory")
; #define PG8_WAIT_L(n) asm volatile("s_waitcnt lgkmcnt(" #n ")" ::: "memory")
; #define PG8_BAR __builtin_amdgcn_s_barrier()
; template <class Epi, class Sched, bool ALIGN_EPI = false, bool SP2 = false>
; __device__ __forceinline__ void gemm_phase(PG8_LAS unsigned char* lds, const Gemm g, const Sched& S, const Epi& E) {
;     ...
;             const bool last = (t == nt - 2);
;             const char* a1 = cA + (size_t)(t + 1) * kstep;
;             const char* a2 = last ? nA : cA + (size_t)(t + 2) * kstep; const char* b2 = last ? nB : cB + (size_t)(t + 2) * kstep;
;             const char* a3 = a2 + kstep; const char* b3 = b2 + kstep;
;             if (last && has_next) S.a_ready(nxt);
;             if constexpr (SP2) {
;             PG8_LDB(B0, 0, 0); PG8_LDB(B1, 0, 1); PG8_SCHED; PG8_LDA(At, 0, 0); PG8_STAGE(PG8_SA(1, 1), a1 + hstep, voffA);
;             PG8_WAIT_V(8); PG8_WAIT_L(0); PG8_BAR; PG8_MMA(0, 0, At, B0); PG8_MMA(0, 1, At, B1); PG8_BAR; PG8_SCHED;
;             PG8_LDA(At, 0, 1); PG8_STAGE(PG8_SB(0, 0), b2, voffB); PG8_STAGE(PG8_SB(0, 1), b2 + hstep, voffB); PG8_STAGE(PG8_SA(0, 0), a2, voffA);
;             PG8_WAIT_V(8); PG8_WAIT_L(0); PG8_BAR; PG8_MMA(1, 0, At, B0); PG8_MMA(1, 1, At, B1); PG8_BAR; PG8_SCHED;
.Lpeel80:
	s_add_u32 s8, s0, 0x100
	s_addc_u32 s9, s1, 0
	s_add_i32 vcc_hi, 0, 0x10000
	s_cmp_eq_u32 vcc_lo, 12
	s_cselect_b32 s13, s66, s9
	s_cselect_b32 s12, s67, s8
	s_cselect_b32 s7, s82, s97
	s_cselect_b32 s6, s83, s96
	s_add_i32 s4, 0, 0x14000
	v_add_u32_e32 v38, vcc_hi, v242
	v_add_u32_e32 v158, s4, v242
	ds_read_b128 v[18:21], v38
	ds_read_b128 v[22:25], v38 offset:1024
	ds_read_b128 v[34:37], v38 offset:2048
	ds_read_b128 v[38:41], v38 offset:3072
	ds_read_b128 v[130:133], v158
	ds_read_b128 v[134:137], v158 offset:1024
	ds_read_b128 v[154:157], v158 offset:2048
	ds_read_b128 v[158:161], v158 offset:3072
	s_add_i32 m0, s11, 0xc000
	ds_read_b128 v[162:165], v243
	ds_read_b128 v[166:169], v243 offset:1024
	ds_read_b128 v[170:173], v243 offset:2048
	ds_read_b128 v[174:177], v243 offset:3072
	ds_read_b128 v[178:181], v243 offset:4096
	ds_read_b128 v[182:185], v243 offset:5120
	ds_read_b128 v[186:189], v243 offset:6144
	ds_read_b128 v[190:193], v243 offset:7168
	global_load_lds_dwordx4 v216, s[0:1]
	s_add_i32 m0, s11, 0xe000
	s_nop 0
	global_load_lds_dwordx4 v218, s[0:1]
	s_waitcnt lgkmcnt(0)
	s_barrier
	s_waitcnt lgkmcnt(0)
	v_mfma_i32_16x16x64_i8 v[150:153], v[18:21], v[162:165], 0
	v_mfma_i32_16x16x64_i8 v[150:153], v[22:25], v[166:169], v[150:153]
	v_mfma_i32_16x16x64_i8 v[146:149], v[38:41], v[166:169], 0
	v_mfma_i32_16x16x64_i8 v[146:149], v[34:37], v[162:165], v[146:149]
	v_mfma_i32_16x16x64_i8 v[110:113], v[34:37], v[170:173], 0
	v_mfma_i32_16x16x64_i8 v[110:113], v[38:41], v[174:177], v[110:113]
	v_mfma_i32_16x16x64_i8 v[118:121], v[22:25], v[174:177], 0
	v_mfma_i32_16x16x64_i8 v[118:121], v[18:21], v[170:173], v[118:121]
	v_mfma_i32_16x16x64_i8 v[54:57], v[18:21], v[178:181], 0
	v_mfma_i32_16x16x64_i8 v[54:57], v[22:25], v[182:185], v[54:57]
	v_mfma_i32_16x16x64_i8 v[30:33], v[38:41], v[182:185], 0
	v_mfma_i32_16x16x64_i8 v[30:33], v[34:37], v[178:181], v[30:33]
	v_mfma_i32_16x16x64_i8 v[58:61], v[34:37], v[186:189], 0
	v_mfma_i32_16x16x64_i8 v[58:61], v[38:41], v[190:193], v[58:61]
	v_mfma_i32_16x16x64_i8 v[94:97], v[22:25], v[190:193], 0
	v_mfma_i32_16x16x64_i8 v[94:97], v[18:21], v[186:189], v[94:97]
	v_mfma_i32_16x16x64_i8 v[62:65], v[154:157], v[186:189], 0
	v_mfma_i32_16x16x64_i8 v[62:65], v[158:161], v[190:193], v[62:65]
	v_mfma_i32_16x16x64_i8 v[138:141], v[158:161], v[166:169], 0
	v_mfma_i32_16x16x64_i8 v[138:141], v[154:157], v[162:165], v[138:141]
	v_mfma_i32_16x16x64_i8 v[142:145], v[130:133], v[162:165], 0
	v_mfma_i32_16x16x64_i8 v[142:145], v[134:137], v[166:169], v[142:145]
	v_mfma_i32_16x16x64_i8 v[102:105], v[134:137], v[174:177], 0
	v_mfma_i32_16x16x64_i8 v[102:105], v[130:133], v[170:173], v[102:105]
	v_mfma_i32_16x16x64_i8 v[98:101], v[154:157], v[170:173], 0
	v_mfma_i32_16x16x64_i8 v[98:101], v[158:161], v[174:177], v[98:101]
	v_mfma_i32_16x16x64_i8 v[26:29], v[158:161], v[182:185], 0
	v_mfma_i32_16x16x64_i8 v[26:29], v[154:157], v[178:181], v[26:29]
	v_mfma_i32_16x16x64_i8 v[42:45], v[130:133], v[178:181], 0
	v_mfma_i32_16x16x64_i8 v[42:45], v[134:137], v[182:185], v[42:45]
	v_mfma_i32_16x16x64_i8 v[78:81], v[134:137], v[190:193], 0
	v_mfma_i32_16x16x64_i8 v[78:81], v[130:133], v[186:189], v[78:81]
	s_barrier
	s_add_i32 s0, vcc_hi, s69
	v_lshl_add_u64 v[198:199], s[6:7], 0, v[0:1]
	s_mov_b32 m0, s0
	ds_read_b128 v[162:165], v243 offset:16384
	ds_read_b128 v[166:169], v243 offset:17408
	ds_read_b128 v[170:173], v243 offset:18432
	ds_read_b128 v[174:177], v243 offset:19456
	ds_read_b128 v[178:181], v243 offset:20480
	ds_read_b128 v[182:185], v243 offset:21504
	ds_read_b128 v[186:189], v243 offset:22528
	ds_read_b128 v[190:193], v243 offset:23552
	global_load_lds_dwordx4 v[198:199], off
	s_add_i32 m0, s0, 0x2000
	s_add_u32 s0, s6, 0x40000
	v_lshl_add_u64 v[200:201], s[6:7], 0, v[214:215]
	s_addc_u32 s1, s7, 0
	s_add_i32 s4, s4, s69
	global_load_lds_dwordx4 v[200:201], off
	s_mov_b32 m0, s4
	v_lshl_add_u64 v[206:207], s[12:13], 0, v[210:211]
	global_load_lds_dwordx4 v0, s[0:1]
	s_add_i32 m0, s4, 0x2000
	v_lshl_add_u64 v[220:221], s[12:13], 0, v[212:213]
	global_load_lds_dwordx4 v214, s[0:1]
	s_mov_b32 m0, s11
	s_nop 0
	global_load_lds_dwordx4 v[206:207], off
	s_mov_b32 m0, s71
	s_nop 0
	global_load_lds_dwordx4 v[220:221], off
	s_waitcnt lgkmcnt(0)
	s_barrier
	s_waitcnt lgkmcnt(0)
	v_mfma_i32_16x16x64_i8 v[106:109], v[18:21], v[162:165], 0
	v_mfma_i32_16x16x64_i8 v[106:109], v[22:25], v[166:169], v[106:109]
	v_mfma_i32_16x16x64_i8 v[46:49], v[34:37], v[162:165], 0
	v_mfma_i32_16x16x64_i8 v[46:49], v[38:41], v[166:169], v[46:49]
	v_mfma_i32_16x16x64_i8 v[6:9], v[34:37], v[170:173], 0
	v_mfma_i32_16x16x64_i8 v[6:9], v[38:41], v[174:177], v[6:9]
	v_mfma_i32_16x16x64_i8 v[14:17], v[18:21], v[170:173], 0
	v_mfma_i32_16x16x64_i8 v[14:17], v[22:25], v[174:177], v[14:17]
	v_mfma_i32_16x16x64_i8 v[90:93], v[18:21], v[178:181], 0
	v_mfma_i32_16x16x64_i8 v[90:93], v[22:25], v[182:185], v[90:93]
	v_mfma_i32_16x16x64_i8 v[86:89], v[34:37], v[178:181], 0
	v_mfma_i32_16x16x64_i8 v[86:89], v[38:41], v[182:185], v[86:89]
	v_mfma_i32_16x16x64_i8 v[18:21], v[18:21], v[186:189], 0
	v_mfma_i32_16x16x64_i8 v[18:21], v[22:25], v[190:193], v[18:21]
	v_mfma_i32_16x16x64_i8 v[22:25], v[34:37], v[186:189], 0
	v_mfma_i32_16x16x64_i8 v[22:25], v[38:41], v[190:193], v[22:25]
	v_mfma_i32_16x16x64_i8 v[38:41], v[154:157], v[162:165], 0
	v_mfma_i32_16x16x64_i8 v[38:41], v[158:161], v[166:169], v[38:41]
	v_mfma_i32_16x16x64_i8 v[2:5], v[154:157], v[170:173], 0
	v_mfma_i32_16x16x64_i8 v[2:5], v[158:161], v[174:177], v[2:5]
	v_mfma_i32_16x16x64_i8 v[10:13], v[130:133], v[170:173], 0
	v_mfma_i32_16x16x64_i8 v[10:13], v[134:137], v[174:177], v[10:13]
	v_mfma_i32_16x16x64_i8 v[50:53], v[130:133], v[178:181], 0
	v_mfma_i32_16x16x64_i8 v[82:85], v[134:137], v[182:185], v[50:53]
	v_mfma_i32_16x16x64_i8 v[34:37], v[130:133], v[162:165], 0
	v_mfma_i32_16x16x64_i8 v[34:37], v[134:137], v[166:169], v[34:37]
	v_mfma_i32_16x16x64_i8 v[50:53], v[154:157], v[178:181], 0
	v_mfma_i32_16x16x64_i8 v[74:77], v[158:161], v[182:185], v[50:53]
	v_mfma_i32_16x16x64_i8 v[50:53], v[130:133], v[186:189], 0
	v_mfma_i32_16x16x64_i8 v[122:125], v[134:137], v[190:193], v[50:53]
	v_mfma_i32_16x16x64_i8 v[50:53], v[154:157], v[186:189], 0
	v_mfma_i32_16x16x64_i8 v[70:73], v[158:161], v[190:193], v[50:53]
	s_barrier
; #define PG8_STAGE(bufoff, gbase, voff) do { _Pragma("unroll") for (int _i = 0; _i < 2; ++_i) \
;         __builtin_amdgcn_global_load_lds((const unsigned*)((const char*)(gbase) + (voff)[_i]), (PG8_LAS unsigned*)(lds + (bufoff) + ldsw + _i * 8192), 16, 0, 0); } while (0)
; #define PG8_LDA(dst, b, h) do { _Pragma("unroll") for (int m = 0; m < 4; ++m) _Pragma("unroll") for (int k = 0; k < 2; ++k) dst[m][k] = *(const PG8_LAS bf16x8*)(lds + PG8_SA(b, h) + aoff + m * 2048 + k * 1024); } while (0)
; #define PG8_LDB(dst, b, h) do { _Pragma("unroll") for (int n = 0; n < 2; ++n) _Pragma("unroll") for (int k = 0; k < 2; ++k) dst[n][k] = *(const PG8_LAS bf16x8*)(lds + PG8_SB(b, h) + boff + n * 2048 + k * 1024); } while (0)
; #define PG8_MMA(ai, bj, At, Bt) do { __builtin_amdgcn_s_setprio(1); _Pragma("unroll") for (int m = 0; m < 4; ++m) _Pragma("unroll") for (int n = 0; n < 2; ++n) _Pragma("unroll") for (int k = 0; k < 2; ++k) \
;         acc[ai][bj][m][n] = mma16<Epi::I8>(Bt[n][k], At[m][k], acc[ai][bj][m][n]); __builtin_amdgcn_s_setprio(0); } while (0)
; #define PG8_WAIT_V(n) asm volatile("s_waitcnt vmcnt(" #n ")" ::: "memory")
; #define PG8_WAIT_L(n) asm volatile("s_waitcnt lgkmcnt(" #n ")" ::: "memory")
; #define PG8_BAR __builtin_amdgcn_s_barrier()
; #define PG8_SCHED __builtin_amdgcn_sched_barrier(0)
; template <class Epi, class Sched, bool ALIGN_EPI = false, bool SP2 = false>
; __device__ __forceinline__ void gemm_phase(PG8_LAS unsigned char* lds, const Gemm g, const Sched& S, const Epi& E) {
;     ...
;             PG8_LDB(B0, 1, 0); PG8_LDB(B1, 1, 1); PG8_SCHED; PG8_LDA(At, 1, 0); PG8_STAGE(PG8_SA(0, 1), a2 + hstep, voffA);
;             PG8_WAIT_V(8); PG8_WAIT_L(0); PG8_BAR; PG8_MMA(0, 0, At, B0); PG8_MMA(0, 1, At, B1); PG8_BAR; PG8_SCHED;
;             PG8_LDA(At, 1, 1); PG8_STAGE(PG8_SB(1, 0), b3, voffB); PG8_STAGE(PG8_SB(1, 1), b3 + hstep, voffB); PG8_STAGE(PG8_SA(1, 0), a3, voffA);
;             PG8_WAIT_V(8); PG8_WAIT_L(0); PG8_BAR; PG8_MMA(1, 0, At, B0); PG8_MMA(1, 1, At, B1); PG8_BAR; PG8_SCHED;
	s_add_i32 s4, 0, 0x18000
	v_add_u32_e32 v126, s4, v242
	s_add_i32 s5, 0, 0x1c000
	ds_read_b128 v[50:53], v126
	ds_read_b128 v[66:69], v126 offset:1024
	ds_read_b128 v[114:117], v126 offset:2048
	ds_read_b128 v[130:133], v126 offset:3072
	v_add_u32_e32 v126, s5, v242
	ds_read_b128 v[134:137], v126
	ds_read_b128 v[154:157], v126 offset:1024
	ds_read_b128 v[158:161], v126 offset:2048
	ds_read_b128 v[162:165], v126 offset:3072
	s_add_u32 s0, s12, 0x40000
	s_addc_u32 s1, s13, 0
	s_mov_b32 m0, s80
	ds_read_b128 v[126:129], v243 offset:32768
	ds_read_b128 v[166:169], v243 offset:33792
	ds_read_b128 v[170:173], v243 offset:34816
	ds_read_b128 v[174:177], v243 offset:35840
	ds_read_b128 v[178:181], v243 offset:36864
	ds_read_b128 v[182:185], v243 offset:37888
	ds_read_b128 v[186:189], v243 offset:38912
	ds_read_b128 v[190:193], v243 offset:39936
	global_load_lds_dwordx4 v210, s[0:1]
	s_mov_b32 m0, s81
	s_nop 0
	global_load_lds_dwordx4 v212, s[0:1]
	s_waitcnt vmcnt(8)
	s_waitcnt lgkmcnt(0)
	s_barrier
	s_waitcnt lgkmcnt(0)
	v_mfma_i32_16x16x64_i8 v[150:153], v[50:53], v[126:129], v[150:153]
	v_mfma_i32_16x16x64_i8 v[150:153], v[66:69], v[166:169], v[150:153]
	v_mfma_i32_16x16x64_i8 v[146:149], v[114:117], v[126:129], v[146:149]
	v_mfma_i32_16x16x64_i8 v[146:149], v[130:133], v[166:169], v[146:149]
	v_mfma_i32_16x16x64_i8 v[110:113], v[114:117], v[170:173], v[110:113]
	v_mfma_i32_16x16x64_i8 v[110:113], v[130:133], v[174:177], v[110:113]
	v_mfma_i32_16x16x64_i8 v[118:121], v[50:53], v[170:173], v[118:121]
	v_mfma_i32_16x16x64_i8 v[118:121], v[66:69], v[174:177], v[118:121]
	v_mfma_i32_16x16x64_i8 v[54:57], v[50:53], v[178:181], v[54:57]
	v_mfma_i32_16x16x64_i8 v[54:57], v[66:69], v[182:185], v[54:57]
	v_mfma_i32_16x16x64_i8 v[30:33], v[114:117], v[178:181], v[30:33]
	v_mfma_i32_16x16x64_i8 v[30:33], v[130:133], v[182:185], v[30:33]
	v_mfma_i32_16x16x64_i8 v[58:61], v[114:117], v[186:189], v[58:61]
	v_mfma_i32_16x16x64_i8 v[58:61], v[130:133], v[190:193], v[58:61]
	v_mfma_i32_16x16x64_i8 v[94:97], v[50:53], v[186:189], v[94:97]
	v_mfma_i32_16x16x64_i8 v[94:97], v[66:69], v[190:193], v[94:97]
	v_mfma_i32_16x16x64_i8 v[142:145], v[134:137], v[126:129], v[142:145]
	v_mfma_i32_16x16x64_i8 v[142:145], v[154:157], v[166:169], v[142:145]
	v_mfma_i32_16x16x64_i8 v[126:129], v[158:161], v[126:129], v[138:141]
	v_mfma_i32_16x16x64_i8 v[138:141], v[162:165], v[166:169], v[126:129]
	v_mfma_i32_16x16x64_i8 v[98:101], v[158:161], v[170:173], v[98:101]
	v_mfma_i32_16x16x64_i8 v[98:101], v[162:165], v[174:177], v[98:101]
	v_mfma_i32_16x16x64_i8 v[102:105], v[134:137], v[170:173], v[102:105]
	v_mfma_i32_16x16x64_i8 v[102:105], v[154:157], v[174:177], v[102:105]
	v_mfma_i32_16x16x64_i8 v[42:45], v[134:137], v[178:181], v[42:45]
	v_mfma_i32_16x16x64_i8 v[42:45], v[154:157], v[182:185], v[42:45]
	v_mfma_i32_16x16x64_i8 v[26:29], v[158:161], v[178:181], v[26:29]
	v_mfma_i32_16x16x64_i8 v[26:29], v[162:165], v[182:185], v[26:29]
	v_mfma_i32_16x16x64_i8 v[62:65], v[158:161], v[186:189], v[62:65]
	v_mfma_i32_16x16x64_i8 v[62:65], v[162:165], v[190:193], v[62:65]
	v_mfma_i32_16x16x64_i8 v[78:81], v[134:137], v[186:189], v[78:81]
	v_mfma_i32_16x16x64_i8 v[78:81], v[154:157], v[190:193], v[78:81]
	s_barrier
	s_add_i32 s0, s4, s69
	v_lshl_add_u64 v[126:127], v[198:199], 0, s[92:93]
	s_mov_b32 m0, s0
	ds_read_b128 v[166:169], v243 offset:49152
	ds_read_b128 v[170:173], v243 offset:50176
	ds_read_b128 v[174:177], v243 offset:51200
	ds_read_b128 v[178:181], v243 offset:52224
	ds_read_b128 v[182:185], v243 offset:53248
	ds_read_b128 v[186:189], v243 offset:54272
	ds_read_b128 v[190:193], v243 offset:55296
	ds_read_b128 v[194:197], v243 offset:56320
	global_load_lds_dwordx4 v[126:127], off
	s_add_i32 m0, s0, 0x2000
	s_add_u32 s0, s6, 0x40080
	v_lshl_add_u64 v[126:127], v[200:201], 0, s[92:93]
	s_addc_u32 s1, s7, 0
	s_add_i32 s4, s5, s69
	global_load_lds_dwordx4 v[126:127], off
	s_mov_b32 m0, s4
	s_nop 0
	global_load_lds_dwordx4 v0, s[0:1]
	s_add_i32 m0, s4, 0x2000
	s_nop 0
	global_load_lds_dwordx4 v214, s[0:1]
	v_lshl_add_u64 v[126:127], v[206:207], 0, s[92:93]
	s_mov_b32 m0, s84
	s_nop 0
	global_load_lds_dwordx4 v[126:127], off
	v_lshl_add_u64 v[126:127], v[220:221], 0, s[92:93]
	s_mov_b32 m0, s85
	s_nop 0
	global_load_lds_dwordx4 v[126:127], off
	s_waitcnt vmcnt(8)
	s_waitcnt lgkmcnt(0)
	s_barrier
	s_waitcnt lgkmcnt(0)
	v_mfma_i32_16x16x64_i8 v[18:21], v[50:53], v[190:193], v[18:21]
	v_mfma_i32_16x16x64_i8 v[126:129], v[66:69], v[194:197], v[18:21]
	v_mfma_i32_16x16x64_i8 v[106:109], v[50:53], v[166:169], v[106:109]
	v_mfma_i32_16x16x64_i8 v[106:109], v[66:69], v[170:173], v[106:109]
	v_mfma_i32_16x16x64_i8 v[46:49], v[114:117], v[166:169], v[46:49]
	v_mfma_i32_16x16x64_i8 v[46:49], v[130:133], v[170:173], v[46:49]
	v_mfma_i32_16x16x64_i8 v[6:9], v[114:117], v[174:177], v[6:9]
	v_mfma_i32_16x16x64_i8 v[6:9], v[130:133], v[178:181], v[6:9]
	v_mfma_i32_16x16x64_i8 v[14:17], v[50:53], v[174:177], v[14:17]
	v_mfma_i32_16x16x64_i8 v[14:17], v[66:69], v[178:181], v[14:17]
	v_mfma_i32_16x16x64_i8 v[90:93], v[50:53], v[182:185], v[90:93]
	v_mfma_i32_16x16x64_i8 v[90:93], v[66:69], v[186:189], v[90:93]
	v_mfma_i32_16x16x64_i8 v[86:89], v[114:117], v[182:185], v[86:89]
	v_mfma_i32_16x16x64_i8 v[86:89], v[130:133], v[186:189], v[86:89]
	v_mfma_i32_16x16x64_i8 v[18:21], v[114:117], v[190:193], v[22:25]
	v_mfma_i32_16x16x64_i8 v[66:69], v[130:133], v[194:197], v[18:21]
	v_mfma_i32_16x16x64_i8 v[18:21], v[134:137], v[166:169], v[34:37]
	v_mfma_i32_16x16x64_i8 v[114:117], v[154:157], v[170:173], v[18:21]
	v_mfma_i32_16x16x64_i8 v[10:13], v[134:137], v[174:177], v[10:13]
	v_mfma_i32_16x16x64_i8 v[10:13], v[154:157], v[178:181], v[10:13]
	v_mfma_i32_16x16x64_i8 v[2:5], v[158:161], v[174:177], v[2:5]
	v_mfma_i32_16x16x64_i8 v[2:5], v[162:165], v[178:181], v[2:5]
	v_mfma_i32_16x16x64_i8 v[18:21], v[158:161], v[166:169], v[38:41]
	v_mfma_i32_16x16x64_i8 v[50:53], v[162:165], v[170:173], v[18:21]
	v_mfma_i32_16x16x64_i8 v[18:21], v[134:137], v[182:185], v[82:85]
	v_mfma_i32_16x16x64_i8 v[82:85], v[154:157], v[186:189], v[18:21]
	v_mfma_i32_16x16x64_i8 v[18:21], v[158:161], v[182:185], v[74:77]
	v_mfma_i32_16x16x64_i8 v[74:77], v[162:165], v[186:189], v[18:21]
	v_mfma_i32_16x16x64_i8 v[18:21], v[134:137], v[190:193], v[122:125]
	v_mfma_i32_16x16x64_i8 v[122:125], v[154:157], v[194:197], v[18:21]
	v_mfma_i32_16x16x64_i8 v[18:21], v[158:161], v[190:193], v[70:73]
	v_mfma_i32_16x16x64_i8 v[70:73], v[162:165], v[194:197], v[18:21]
	s_barrier
	s_add_i32 vcc_lo, vcc_lo, 2
	s_add_u32 s96, s96, 0x100
	s_addc_u32 s97, s97, 0
	s_cmp_gt_u32 vcc_lo, 13
	s_mov_b64 s[0:1], s[8:9]
	s_cbranch_scc0 .LBB0_80
	s_branch .Lpeelx80

; #define PG8_STAGE(bufoff, gbase, voff) do { _Pragma("unroll") for (int _i = 0; _i < 2; ++_i) \
;         __builtin_amdgcn_global_load_lds((const unsigned*)((const char*)(gbase) + (voff)[_i]), (PG8_LAS unsigned*)(lds + (bufoff) + ldsw + _i * 8192), 16, 0, 0); } while (0)
; #define PG8_WAIT_V(n) asm volatile("s_waitcnt vmcnt(" #n ")" ::: "memory")
; #define PG8_BAR __builtin_amdgcn_s_barrier()
; template <class Epi, class Sched, bool ALIGN_EPI = false, bool SP2 = false>
; __device__ __forceinline__ void gemm_phase(PG8_LAS unsigned char* lds, const Gemm g, const Sched& S, const Epi& E) {
;     int tid_ = threadIdx.x; asm volatile("" : "+v"(tid_)); const int tid = tid_, wid = __builtin_amdgcn_readfirstlane(tid >> 6), lane = tid & 63, wr = wid >> 2, wc = wid & 3, fr = lane & 15, fq = lane >> 4;
;     const int K = g.K, nt = K / BK;
;     unsigned voffA[2], voffB[2];
; #pragma unroll
;     for (int i = 0; i < 2; ++i) { int R, C; stage_rc(tid * 16 + i * 8192, R, C); const int Rb = Epi::PERM ? ((R & ~31) + perm32(R & 31)) : R;
;         const int Ra = Epi::APERM ? ((R & ~63) + ((R & 15) << 2) + ((R >> 4) & 3)) : R;
;         voffA[i] = (unsigned)(Ra * K + C) * 2u; voffB[i] = (unsigned)(Rb * K + C) * 2u; }
;     const size_t kstep = (size_t)(BK * 2);
;     const size_t hstep = (size_t)HALF * K * 2;
;     const size_t tstep = 2 * hstep;
;     const unsigned ldsw = (unsigned)wid * 1024u;
;     const int aoff = lds_byte(wr * 64 + fr, fq * 8), boff = lds_byte(wc * 32 + fr, fq * 8);
;     ...
;     if constexpr (SP2) {
;         PG8_STAGE(PG8_SB(0, 0), cB, voffB); PG8_STAGE(PG8_SB(0, 1), cB + hstep, voffB); PG8_STAGE(PG8_SA(0, 0), cA, voffA); PG8_STAGE(PG8_SA(0, 1), cA + hstep, voffA);
;         if (wr == 1) PG8_BAR;
;         PG8_WAIT_V(2); PG8_BAR;
;         PG8_STAGE(PG8_SB(1, 0), cB + kstep, voffB); PG8_STAGE(PG8_SA(1, 0), cA + kstep, voffA); PG8_STAGE(PG8_SB(1, 1), cB + hstep + kstep, voffB);
;         PG8_WAIT_V(6); PG8_BAR;
.LBB0_165:
	v_readlane_b32 s16, v254, 36
	v_readlane_b32 s17, v254, 37
	s_cmp_lt_i32 s16, 26
	s_cselect_b64 s[84:85], -1, 0
	v_readlane_b32 s16, v252, 37
	s_or_b64 s[0:1], s[84:85], s[0:1]
	v_readlane_b32 s17, v252, 38
	s_and_b64 s[0:1], s[16:17], s[0:1]
	s_and_b64 s[0:1], s[0:1], exec
	s_cselect_b32 s82, s13, -1
	s_lshl_b32 s0, s4, 6
	v_and_b32_e32 v21, 48, v20
	v_lshlrev_b32_e32 v22, 6, v20
	s_movk_i32 s1, 0x3c0
	v_lshlrev_b32_e32 v20, 2, v20
	v_readlane_b32 s18, v254, 38
	v_readlane_b32 s19, v254, 39
	s_and_b32 s43, s5, 3
	v_writelane_b32 v254, s0, 42
	s_lshl_b32 s0, s4, 13
	v_and_or_b32 v21, v22, s1, v21
	v_and_b32_e32 v20, 32, v20
	v_bitop3_b32 v22, v21, s0, v20 bitop3:0xde
	s_lshl_b32 s0, s43, 12
	v_bitop3_b32 v248, v21, s0, v20 bitop3:0xde
	s_mul_i32 s0, s37, 0xc000
	s_add_i32 s0, s0, s10
	s_ashr_i32 s1, s0, 31
	s_lshr_b32 s69, s11, 6
	s_lshl_b32 s36, s43, 5
	s_lshl_b64 s[0:1], s[0:1], 3
	s_add_u32 s44, s34, s0
	s_addc_u32 s45, s35, s1
	s_add_i32 m0, s81, 0x18000
	v_lshl_add_u64 v[2:3], v[2:3], 0, s[98:99]
	s_waitcnt vmcnt(2)
	s_barrier
	global_load_lds_dwordx4 v[2:3], off
	v_lshl_add_u64 v[2:3], v[4:5], 0, s[98:99]
	s_add_i32 m0, s81, 0x1a000
	s_add_i32 s10, s81, 0x8000
	global_load_lds_dwordx4 v[2:3], off
	v_lshl_add_u64 v[2:3], v[10:11], 0, s[98:99]
	s_mov_b32 m0, s10
	s_add_i32 s11, s81, 0xa000
	global_load_lds_dwordx4 v[2:3], off
	v_lshl_add_u64 v[2:3], v[12:13], 0, s[98:99]
	s_mov_b32 m0, s11
	s_add_i32 s13, s69, -2
	global_load_lds_dwordx4 v[2:3], off
	s_add_i32 m0, s81, 0x1c000
	v_lshl_add_u64 v[2:3], v[6:7], 0, s[98:99]
	global_load_lds_dwordx4 v[2:3], off
	v_lshl_add_u64 v[2:3], v[8:9], 0, s[98:99]
	s_add_i32 m0, s81, 0x1e000
	s_cmpk_lt_u32 s67, 0x100
	global_load_lds_dwordx4 v[2:3], off
	s_cselect_b64 s[46:47], -1, 0
	s_ashr_i32 s39, s23, 31
	s_cmp_gt_i32 s82, -1
	s_cselect_b64 s[48:49], -1, 0
	s_mul_hi_u32 s4, s82, 0x6000
	s_mul_i32 s5, s82, 0x6000
	s_and_b64 s[0:1], s[48:49], exec
	s_cselect_b32 s1, s4, 0
	s_cselect_b32 s0, s5, 0
	s_lshl_b64 s[0:1], s[0:1], 2
	v_readlane_b32 s16, v252, 52
	v_readlane_b32 s17, v252, 53
	s_add_u32 s50, s16, s0
	s_addc_u32 s51, s17, s1
	v_readlane_b32 s0, v252, 54
	v_add_u32_e32 v2, v16, v14
	s_add_u32 s0, s0, s5
	v_add_lshl_u32 v2, v2, v15, 1
	v_mov_b32_e32 v3, v1
	s_waitcnt vmcnt(0)
	v_writelane_b32 v254, s0, 44
	v_readlane_b32 s0, v252, 55
	v_lshl_add_u64 v[200:201], s[58:59], 0, v[2:3]
	v_add_u32_e32 v2, v19, v17
	s_addc_u32 s0, s0, s4
	v_add_lshl_u32 v2, v2, v18, 1
	s_mov_b32 s82, 0
	v_writelane_b32 v254, s0, 50
	v_lshl_add_u64 v[210:211], s[58:59], 0, v[2:3]
	s_cmp_lg_u32 s98, 0x8000
	s_cbranch_scc1 .Ltl_c
	v_add_u32_e32 v200, 0x4000, v194
	v_mov_b32_e32 v201, 0
	v_add_u32_e32 v210, 0x4000, v196
	v_mov_b32_e32 v211, 0

; #define PG8_STAGE(bufoff, gbase, voff) do { _Pragma("unroll") for (int _i = 0; _i < 2; ++_i) \
;         __builtin_amdgcn_global_load_lds((const unsigned*)((const char*)(gbase) + (voff)[_i]), (PG8_LAS unsigned*)(lds + (bufoff) + ldsw + _i * 8192), 16, 0, 0); } while (0)
; #define PG8_LDA(dst, b, h) do { _Pragma("unroll") for (int m = 0; m < 4; ++m) _Pragma("unroll") for (int k = 0; k < 2; ++k) dst[m][k] = *(const PG8_LAS bf16x8*)(lds + PG8_SA(b, h) + aoff + m * 2048 + k * 1024); } while (0)
; #define PG8_LDB(dst, b, h) do { _Pragma("unroll") for (int n = 0; n < 2; ++n) _Pragma("unroll") for (int k = 0; k < 2; ++k) dst[n][k] = *(const PG8_LAS bf16x8*)(lds + PG8_SB(b, h) + boff + n * 2048 + k * 1024); } while (0)
; #define PG8_MMA(ai, bj, At, Bt) do { __builtin_amdgcn_s_setprio(1); _Pragma("unroll") for (int m = 0; m < 4; ++m) _Pragma("unroll") for (int n = 0; n < 2; ++n) _Pragma("unroll") for (int k = 0; k < 2; ++k) \
;         acc[ai][bj][m][n] = mma16<Epi::I8>(Bt[n][k], At[m][k], acc[ai][bj][m][n]); __builtin_amdgcn_s_setprio(0); } while (0)
; #define PG8_WAIT_V(n) asm volatile("s_waitcnt vmcnt(" #n ")" ::: "memory")
; #define PG8_WAIT_L(n) asm volatile("s_waitcnt lgkmcnt(" #n ")" ::: "memory")
; #define PG8_BAR __builtin_amdgcn_s_barrier()
; template <class Epi, class Sched, bool ALIGN_EPI = false, bool SP2 = false>
; __device__ __forceinline__ void gemm_phase(PG8_LAS unsigned char* lds, const Gemm g, const Sched& S, const Epi& E) {
;     ...
;             const bool last = (t == nt - 2);
;             const char* a1 = cA + (size_t)(t + 1) * kstep;
;             const char* a2 = last ? nA : cA + (size_t)(t + 2) * kstep; const char* b2 = last ? nB : cB + (size_t)(t + 2) * kstep;
;             const char* a3 = a2 + kstep; const char* b3 = b2 + kstep;
;             if (last && has_next) S.a_ready(nxt);
;             if constexpr (SP2) {
;             PG8_LDB(B0, 0, 0); PG8_LDB(B1, 0, 1); PG8_SCHED; PG8_LDA(At, 0, 0); PG8_STAGE(PG8_SA(1, 1), a1 + hstep, voffA);
;             PG8_WAIT_V(8); PG8_WAIT_L(0); PG8_BAR; PG8_MMA(0, 0, At, B0); PG8_MMA(0, 1, At, B1); PG8_BAR; PG8_SCHED;
;             PG8_LDA(At, 0, 1); PG8_STAGE(PG8_SB(0, 0), b2, voffB); PG8_STAGE(PG8_SB(0, 1), b2 + hstep, voffB); PG8_STAGE(PG8_SA(0, 0), a2, voffA);
;             PG8_WAIT_V(8); PG8_WAIT_L(0); PG8_BAR; PG8_MMA(1, 0, At, B0); PG8_MMA(1, 1, At, B1); PG8_BAR; PG8_SCHED;
.Lpeel175:
	s_add_i32 vcc_lo, s8, 2
	s_add_u32 s4, s6, s98
	s_addc_u32 s5, s7, 0
	s_add_i32 vcc_hi, 0, 0x10000
	s_cmp_eq_u32 s13, s8
	s_cselect_b32 s9, s1, s5
	s_cselect_b32 s8, s0, s4
	s_cselect_b32 s5, s97, s85
	s_cselect_b32 s4, s96, s67
	s_add_i32 s84, 0, 0x14000
	v_add_u32_e32 v122, vcc_hi, v248
	v_add_u32_e32 v154, s84, v248
	ds_read_b128 v[98:101], v122
	ds_read_b128 v[102:105], v122 offset:1024
	ds_read_b128 v[114:117], v122 offset:2048
	ds_read_b128 v[122:125], v122 offset:3072
	ds_read_b128 v[130:133], v154
	ds_read_b128 v[138:141], v154 offset:1024
	ds_read_b128 v[146:149], v154 offset:2048
	ds_read_b128 v[154:157], v154 offset:3072
	v_lshl_add_u64 v[206:207], s[6:7], 0, v[200:201]
	s_add_i32 m0, s81, 0xc000
	ds_read_b128 v[162:165], v249
	ds_read_b128 v[166:169], v249 offset:1024
	ds_read_b128 v[170:173], v249 offset:2048
	ds_read_b128 v[174:177], v249 offset:3072
	ds_read_b128 v[178:181], v249 offset:4096
	ds_read_b128 v[182:185], v249 offset:5120
	ds_read_b128 v[186:189], v249 offset:6144
	ds_read_b128 v[190:193], v249 offset:7168
	global_load_lds_dwordx4 v[206:207], off
	v_lshl_add_u64 v[206:207], s[6:7], 0, v[210:211]
	s_add_i32 m0, s81, 0xe000
	s_nop 0
	global_load_lds_dwordx4 v[206:207], off
	s_waitcnt lgkmcnt(0)
	s_barrier
	s_waitcnt lgkmcnt(0)
	v_mfma_f32_16x16x32_bf16 v[158:161], v[98:101], v[162:165], 0
	v_mfma_f32_16x16x32_bf16 v[158:161], v[102:105], v[166:169], v[158:161]
	v_mfma_f32_16x16x32_bf16 v[150:153], v[114:117], v[162:165], 0
	v_mfma_f32_16x16x32_bf16 v[150:153], v[122:125], v[166:169], v[150:153]
	v_mfma_f32_16x16x32_bf16 v[118:121], v[114:117], v[170:173], 0
	v_mfma_f32_16x16x32_bf16 v[118:121], v[122:125], v[174:177], v[118:121]
	v_mfma_f32_16x16x32_bf16 v[126:129], v[98:101], v[170:173], 0
	v_mfma_f32_16x16x32_bf16 v[126:129], v[102:105], v[174:177], v[126:129]
	v_mfma_f32_16x16x32_bf16 v[94:97], v[98:101], v[178:181], 0
	v_mfma_f32_16x16x32_bf16 v[94:97], v[102:105], v[182:185], v[94:97]
	v_mfma_f32_16x16x32_bf16 v[90:93], v[114:117], v[178:181], 0
	v_mfma_f32_16x16x32_bf16 v[90:93], v[122:125], v[182:185], v[90:93]
	v_mfma_f32_16x16x32_bf16 v[74:77], v[114:117], v[186:189], 0
	v_mfma_f32_16x16x32_bf16 v[74:77], v[122:125], v[190:193], v[74:77]
	v_mfma_f32_16x16x32_bf16 v[78:81], v[98:101], v[186:189], 0
	v_mfma_f32_16x16x32_bf16 v[78:81], v[102:105], v[190:193], v[78:81]
	v_mfma_f32_16x16x32_bf16 v[142:145], v[130:133], v[162:165], 0
	v_mfma_f32_16x16x32_bf16 v[142:145], v[138:141], v[166:169], v[142:145]
	v_mfma_f32_16x16x32_bf16 v[134:137], v[146:149], v[162:165], 0
	v_mfma_f32_16x16x32_bf16 v[134:137], v[154:157], v[166:169], v[134:137]
	v_mfma_f32_16x16x32_bf16 v[106:109], v[146:149], v[170:173], 0
	v_mfma_f32_16x16x32_bf16 v[106:109], v[154:157], v[174:177], v[106:109]
	v_mfma_f32_16x16x32_bf16 v[110:113], v[130:133], v[170:173], 0
	v_mfma_f32_16x16x32_bf16 v[110:113], v[138:141], v[174:177], v[110:113]
	v_mfma_f32_16x16x32_bf16 v[86:89], v[130:133], v[178:181], 0
	v_mfma_f32_16x16x32_bf16 v[86:89], v[138:141], v[182:185], v[86:89]
	v_mfma_f32_16x16x32_bf16 v[82:85], v[146:149], v[178:181], 0
	v_mfma_f32_16x16x32_bf16 v[82:85], v[154:157], v[182:185], v[82:85]
	v_mfma_f32_16x16x32_bf16 v[66:69], v[146:149], v[186:189], 0
	v_mfma_f32_16x16x32_bf16 v[66:69], v[154:157], v[190:193], v[66:69]
	v_mfma_f32_16x16x32_bf16 v[70:73], v[130:133], v[186:189], 0
	v_mfma_f32_16x16x32_bf16 v[70:73], v[138:141], v[190:193], v[70:73]
	s_barrier
	s_add_i32 vcc_hi, vcc_hi, s80
	v_lshl_add_u64 v[206:207], s[4:5], 0, v[0:1]
	s_mov_b32 m0, vcc_hi
	ds_read_b128 v[162:165], v249 offset:16384
	ds_read_b128 v[166:169], v249 offset:17408
	ds_read_b128 v[170:173], v249 offset:18432
	ds_read_b128 v[174:177], v249 offset:19456
	ds_read_b128 v[178:181], v249 offset:20480
	ds_read_b128 v[182:185], v249 offset:21504
	ds_read_b128 v[186:189], v249 offset:22528
	ds_read_b128 v[190:193], v249 offset:23552
	global_load_lds_dwordx4 v[206:207], off
	s_add_i32 m0, vcc_hi, 0x2000
	v_lshl_add_u64 v[212:213], s[4:5], 0, v[198:199]
	s_add_u32 s4, s4, s100
	s_addc_u32 s5, s5, 0
	s_add_i32 s84, s84, s80
	global_load_lds_dwordx4 v[212:213], off
	v_lshl_add_u64 v[214:215], s[4:5], 0, v[0:1]
	s_mov_b32 m0, s84
	v_lshl_add_u64 v[216:217], s[4:5], 0, v[198:199]
	global_load_lds_dwordx4 v[214:215], off
	s_add_i32 m0, s84, 0x2000
	v_lshl_add_u64 v[218:219], s[8:9], 0, v[194:195]
	global_load_lds_dwordx4 v[216:217], off
	s_mov_b32 m0, s81
	v_lshl_add_u64 v[220:221], s[8:9], 0, v[196:197]
	global_load_lds_dwordx4 v[218:219], off
	s_mov_b32 m0, s70
	s_nop 0
	global_load_lds_dwordx4 v[220:221], off
	s_waitcnt lgkmcnt(0)
	s_barrier
; #define PG8_STAGE(bufoff, gbase, voff) do { _Pragma("unroll") for (int _i = 0; _i < 2; ++_i) \
;         __builtin_amdgcn_global_load_lds((const unsigned*)((const char*)(gbase) + (voff)[_i]), (PG8_LAS unsigned*)(lds + (bufoff) + ldsw + _i * 8192), 16, 0, 0); } while (0)
; #define PG8_LDA(dst, b, h) do { _Pragma("unroll") for (int m = 0; m < 4; ++m) _Pragma("unroll") for (int k = 0; k < 2; ++k) dst[m][k] = *(const PG8_LAS bf16x8*)(lds + PG8_SA(b, h) + aoff + m * 2048 + k * 1024); } while (0)
; #define PG8_LDB(dst, b, h) do { _Pragma("unroll") for (int n = 0; n < 2; ++n) _Pragma("unroll") for (int k = 0; k < 2; ++k) dst[n][k] = *(const PG8_LAS bf16x8*)(lds + PG8_SB(b, h) + boff + n * 2048 + k * 1024); } while (0)
; #define PG8_MMA(ai, bj, At, Bt) do { __builtin_amdgcn_s_setprio(1); _Pragma("unroll") for (int m = 0; m < 4; ++m) _Pragma("unroll") for (int n = 0; n < 2; ++n) _Pragma("unroll") for (int k = 0; k < 2; ++k) \
;         acc[ai][bj][m][n] = mma16<Epi::I8>(Bt[n][k], At[m][k], acc[ai][bj][m][n]); __builtin_amdgcn_s_setprio(0); } while (0)
; #define PG8_WAIT_V(n) asm volatile("s_waitcnt vmcnt(" #n ")" ::: "memory")
; #define PG8_WAIT_L(n) asm volatile("s_waitcnt lgkmcnt(" #n ")" ::: "memory")
; #define PG8_BAR __builtin_amdgcn_s_barrier()
; #define PG8_SCHED __builtin_amdgcn_sched_barrier(0)
; template <class Epi, class Sched, bool ALIGN_EPI = false, bool SP2 = false>
; __device__ __forceinline__ void gemm_phase(PG8_LAS unsigned char* lds, const Gemm g, const Sched& S, const Epi& E) {
;     ...
;             PG8_WAIT_V(8); PG8_WAIT_L(0); PG8_BAR; PG8_MMA(1, 0, At, B0); PG8_MMA(1, 1, At, B1); PG8_BAR; PG8_SCHED;
;             PG8_LDB(B0, 1, 0); PG8_LDB(B1, 1, 1); PG8_SCHED; PG8_LDA(At, 1, 0); PG8_STAGE(PG8_SA(0, 1), a2 + hstep, voffA);
;             PG8_WAIT_V(8); PG8_WAIT_L(0); PG8_BAR; PG8_MMA(0, 0, At, B0); PG8_MMA(0, 1, At, B1); PG8_BAR; PG8_SCHED;
	s_waitcnt lgkmcnt(0)
	v_mfma_f32_16x16x32_bf16 v[62:65], v[98:101], v[162:165], 0
	v_mfma_f32_16x16x32_bf16 v[62:65], v[102:105], v[166:169], v[62:65]
	v_mfma_f32_16x16x32_bf16 v[58:61], v[114:117], v[162:165], 0
	v_mfma_f32_16x16x32_bf16 v[58:61], v[122:125], v[166:169], v[58:61]
	v_mfma_f32_16x16x32_bf16 v[42:45], v[114:117], v[170:173], 0
	v_mfma_f32_16x16x32_bf16 v[42:45], v[122:125], v[174:177], v[42:45]
	v_mfma_f32_16x16x32_bf16 v[46:49], v[98:101], v[170:173], 0
	v_mfma_f32_16x16x32_bf16 v[46:49], v[102:105], v[174:177], v[46:49]
	v_mfma_f32_16x16x32_bf16 v[30:33], v[98:101], v[178:181], 0
	v_mfma_f32_16x16x32_bf16 v[30:33], v[102:105], v[182:185], v[30:33]
	v_mfma_f32_16x16x32_bf16 v[26:29], v[114:117], v[178:181], 0
	v_mfma_f32_16x16x32_bf16 v[26:29], v[122:125], v[182:185], v[26:29]
	v_mfma_f32_16x16x32_bf16 v[10:13], v[114:117], v[186:189], 0
	v_mfma_f32_16x16x32_bf16 v[10:13], v[122:125], v[190:193], v[10:13]
	v_mfma_f32_16x16x32_bf16 v[14:17], v[98:101], v[186:189], 0
	v_mfma_f32_16x16x32_bf16 v[14:17], v[102:105], v[190:193], v[14:17]
	v_mfma_f32_16x16x32_bf16 v[54:57], v[130:133], v[162:165], 0
	v_mfma_f32_16x16x32_bf16 v[54:57], v[138:141], v[166:169], v[54:57]
	v_mfma_f32_16x16x32_bf16 v[50:53], v[146:149], v[162:165], 0
	v_mfma_f32_16x16x32_bf16 v[50:53], v[154:157], v[166:169], v[50:53]
	v_mfma_f32_16x16x32_bf16 v[34:37], v[146:149], v[170:173], 0
	v_mfma_f32_16x16x32_bf16 v[34:37], v[154:157], v[174:177], v[34:37]
	v_mfma_f32_16x16x32_bf16 v[38:41], v[130:133], v[170:173], 0
	v_mfma_f32_16x16x32_bf16 v[38:41], v[138:141], v[174:177], v[38:41]
	v_mfma_f32_16x16x32_bf16 v[22:25], v[130:133], v[178:181], 0
	v_mfma_f32_16x16x32_bf16 v[22:25], v[138:141], v[182:185], v[22:25]
	v_mfma_f32_16x16x32_bf16 v[18:21], v[146:149], v[178:181], 0
	v_mfma_f32_16x16x32_bf16 v[18:21], v[154:157], v[182:185], v[18:21]
	v_mfma_f32_16x16x32_bf16 v[2:5], v[146:149], v[186:189], 0
	v_mfma_f32_16x16x32_bf16 v[2:5], v[154:157], v[190:193], v[2:5]
	v_mfma_f32_16x16x32_bf16 v[6:9], v[130:133], v[186:189], 0
	v_mfma_f32_16x16x32_bf16 v[6:9], v[138:141], v[190:193], v[6:9]
	s_barrier
	s_add_i32 s84, 0, 0x18000
	s_add_i32 vcc_hi, 0, 0x1c000
	v_add_u32_e32 v122, s84, v248
	v_add_u32_e32 v154, vcc_hi, v248
	ds_read_b128 v[98:101], v122
	ds_read_b128 v[102:105], v122 offset:1024
	ds_read_b128 v[114:117], v122 offset:2048
	ds_read_b128 v[122:125], v122 offset:3072
	ds_read_b128 v[130:133], v154
	ds_read_b128 v[138:141], v154 offset:1024
	ds_read_b128 v[146:149], v154 offset:2048
	ds_read_b128 v[154:157], v154 offset:3072
	s_add_u32 s4, s8, s100
	s_addc_u32 s5, s9, 0
	s_mov_b32 m0, s71
	v_lshl_add_u64 v[222:223], s[4:5], 0, v[194:195]
	ds_read_b128 v[162:165], v249 offset:32768
	ds_read_b128 v[166:169], v249 offset:33792
	ds_read_b128 v[170:173], v249 offset:34816
	ds_read_b128 v[174:177], v249 offset:35840
	ds_read_b128 v[178:181], v249 offset:36864
	ds_read_b128 v[182:185], v249 offset:37888
	ds_read_b128 v[186:189], v249 offset:38912
	ds_read_b128 v[190:193], v249 offset:39936
	global_load_lds_dwordx4 v[222:223], off
	v_lshl_add_u64 v[222:223], s[4:5], 0, v[196:197]
	s_mov_b32 m0, s12
	s_nop 0
	global_load_lds_dwordx4 v[222:223], off
	s_waitcnt vmcnt(8)
	s_waitcnt lgkmcnt(0)
	s_barrier
	s_waitcnt lgkmcnt(0)
	v_mfma_f32_16x16x32_bf16 v[158:161], v[98:101], v[162:165], v[158:161]
	v_mfma_f32_16x16x32_bf16 v[158:161], v[102:105], v[166:169], v[158:161]
	v_mfma_f32_16x16x32_bf16 v[150:153], v[114:117], v[162:165], v[150:153]
	v_mfma_f32_16x16x32_bf16 v[150:153], v[122:125], v[166:169], v[150:153]
	v_mfma_f32_16x16x32_bf16 v[118:121], v[114:117], v[170:173], v[118:121]
	v_mfma_f32_16x16x32_bf16 v[118:121], v[122:125], v[174:177], v[118:121]
	v_mfma_f32_16x16x32_bf16 v[126:129], v[98:101], v[170:173], v[126:129]
	v_mfma_f32_16x16x32_bf16 v[126:129], v[102:105], v[174:177], v[126:129]
	v_mfma_f32_16x16x32_bf16 v[94:97], v[98:101], v[178:181], v[94:97]
	v_mfma_f32_16x16x32_bf16 v[94:97], v[102:105], v[182:185], v[94:97]
	v_mfma_f32_16x16x32_bf16 v[90:93], v[114:117], v[178:181], v[90:93]
	v_mfma_f32_16x16x32_bf16 v[90:93], v[122:125], v[182:185], v[90:93]
	v_mfma_f32_16x16x32_bf16 v[74:77], v[114:117], v[186:189], v[74:77]
	v_mfma_f32_16x16x32_bf16 v[74:77], v[122:125], v[190:193], v[74:77]
	v_mfma_f32_16x16x32_bf16 v[78:81], v[98:101], v[186:189], v[78:81]
	v_mfma_f32_16x16x32_bf16 v[78:81], v[102:105], v[190:193], v[78:81]
	v_mfma_f32_16x16x32_bf16 v[142:145], v[130:133], v[162:165], v[142:145]
	v_mfma_f32_16x16x32_bf16 v[142:145], v[138:141], v[166:169], v[142:145]
	v_mfma_f32_16x16x32_bf16 v[134:137], v[146:149], v[162:165], v[134:137]
	v_mfma_f32_16x16x32_bf16 v[134:137], v[154:157], v[166:169], v[134:137]
	v_mfma_f32_16x16x32_bf16 v[106:109], v[146:149], v[170:173], v[106:109]
	v_mfma_f32_16x16x32_bf16 v[106:109], v[154:157], v[174:177], v[106:109]
	v_mfma_f32_16x16x32_bf16 v[110:113], v[130:133], v[170:173], v[110:113]
	v_mfma_f32_16x16x32_bf16 v[110:113], v[138:141], v[174:177], v[110:113]
	v_mfma_f32_16x16x32_bf16 v[86:89], v[130:133], v[178:181], v[86:89]
	v_mfma_f32_16x16x32_bf16 v[86:89], v[138:141], v[182:185], v[86:89]
	v_mfma_f32_16x16x32_bf16 v[82:85], v[146:149], v[178:181], v[82:85]
	v_mfma_f32_16x16x32_bf16 v[82:85], v[154:157], v[182:185], v[82:85]
	v_mfma_f32_16x16x32_bf16 v[66:69], v[146:149], v[186:189], v[66:69]
	v_mfma_f32_16x16x32_bf16 v[66:69], v[154:157], v[190:193], v[66:69]
	v_mfma_f32_16x16x32_bf16 v[70:73], v[130:133], v[186:189], v[70:73]
	v_mfma_f32_16x16x32_bf16 v[70:73], v[138:141], v[190:193], v[70:73]
	s_barrier
; #define PG8_STAGE(bufoff, gbase, voff) do { _Pragma("unroll") for (int _i = 0; _i < 2; ++_i) \
;         __builtin_amdgcn_global_load_lds((const unsigned*)((const char*)(gbase) + (voff)[_i]), (PG8_LAS unsigned*)(lds + (bufoff) + ldsw + _i * 8192), 16, 0, 0); } while (0)
; #define PG8_LDA(dst, b, h) do { _Pragma("unroll") for (int m = 0; m < 4; ++m) _Pragma("unroll") for (int k = 0; k < 2; ++k) dst[m][k] = *(const PG8_LAS bf16x8*)(lds + PG8_SA(b, h) + aoff + m * 2048 + k * 1024); } while (0)
; #define PG8_MMA(ai, bj, At, Bt) do { __builtin_amdgcn_s_setprio(1); _Pragma("unroll") for (int m = 0; m < 4; ++m) _Pragma("unroll") for (int n = 0; n < 2; ++n) _Pragma("unroll") for (int k = 0; k < 2; ++k) \
;         acc[ai][bj][m][n] = mma16<Epi::I8>(Bt[n][k], At[m][k], acc[ai][bj][m][n]); __builtin_amdgcn_s_setprio(0); } while (0)
; #define PG8_WAIT_V(n) asm volatile("s_waitcnt vmcnt(" #n ")" ::: "memory")
; #define PG8_WAIT_L(n) asm volatile("s_waitcnt lgkmcnt(" #n ")" ::: "memory")
; #define PG8_BAR __builtin_amdgcn_s_barrier()
; #define PG8_SCHED __builtin_amdgcn_sched_barrier(0)
; template <class Epi, class Sched, bool ALIGN_EPI = false, bool SP2 = false>
; __device__ __forceinline__ void gemm_phase(PG8_LAS unsigned char* lds, const Gemm g, const Sched& S, const Epi& E) {
;     ...
;             PG8_LDA(At, 1, 1); PG8_STAGE(PG8_SB(1, 0), b3, voffB); PG8_STAGE(PG8_SB(1, 1), b3 + hstep, voffB); PG8_STAGE(PG8_SA(1, 0), a3, voffA);
;             PG8_WAIT_V(8); PG8_WAIT_L(0); PG8_BAR; PG8_MMA(1, 0, At, B0); PG8_MMA(1, 1, At, B1); PG8_BAR; PG8_SCHED;
	s_add_i32 s4, s84, s80
	v_lshl_add_u64 v[206:207], v[206:207], 0, s[98:99]
	s_mov_b32 m0, s4
	ds_read_b128 v[162:165], v249 offset:49152
	ds_read_b128 v[166:169], v249 offset:50176
	ds_read_b128 v[170:173], v249 offset:51200
	ds_read_b128 v[174:177], v249 offset:52224
	ds_read_b128 v[178:181], v249 offset:53248
	ds_read_b128 v[182:185], v249 offset:54272
	ds_read_b128 v[186:189], v249 offset:55296
	ds_read_b128 v[190:193], v249 offset:56320
	global_load_lds_dwordx4 v[206:207], off
	v_lshl_add_u64 v[206:207], v[212:213], 0, s[98:99]
	s_add_i32 m0, s4, 0x2000
	s_add_i32 s4, vcc_hi, s80
	global_load_lds_dwordx4 v[206:207], off
	v_lshl_add_u64 v[206:207], v[214:215], 0, s[98:99]
	s_mov_b32 m0, s4
	s_nop 0
	global_load_lds_dwordx4 v[206:207], off
	v_lshl_add_u64 v[206:207], v[216:217], 0, s[98:99]
	s_add_i32 m0, s4, 0x2000
	s_nop 0
	global_load_lds_dwordx4 v[206:207], off
	v_lshl_add_u64 v[206:207], v[218:219], 0, s[98:99]
	s_mov_b32 m0, s10
	s_nop 0
	global_load_lds_dwordx4 v[206:207], off
	v_lshl_add_u64 v[206:207], v[220:221], 0, s[98:99]
	s_mov_b32 m0, s11
	s_nop 0
	global_load_lds_dwordx4 v[206:207], off
	s_waitcnt vmcnt(8)
	s_waitcnt lgkmcnt(0)
	s_barrier
	s_waitcnt lgkmcnt(0)
	v_mfma_f32_16x16x32_bf16 v[62:65], v[98:101], v[162:165], v[62:65]
	v_mfma_f32_16x16x32_bf16 v[62:65], v[102:105], v[166:169], v[62:65]
	v_mfma_f32_16x16x32_bf16 v[58:61], v[114:117], v[162:165], v[58:61]
	v_mfma_f32_16x16x32_bf16 v[58:61], v[122:125], v[166:169], v[58:61]
	v_mfma_f32_16x16x32_bf16 v[42:45], v[114:117], v[170:173], v[42:45]
	v_mfma_f32_16x16x32_bf16 v[42:45], v[122:125], v[174:177], v[42:45]
	v_mfma_f32_16x16x32_bf16 v[46:49], v[98:101], v[170:173], v[46:49]
	v_mfma_f32_16x16x32_bf16 v[46:49], v[102:105], v[174:177], v[46:49]
	v_mfma_f32_16x16x32_bf16 v[30:33], v[98:101], v[178:181], v[30:33]
	v_mfma_f32_16x16x32_bf16 v[30:33], v[102:105], v[182:185], v[30:33]
	v_mfma_f32_16x16x32_bf16 v[26:29], v[114:117], v[178:181], v[26:29]
	v_mfma_f32_16x16x32_bf16 v[26:29], v[122:125], v[182:185], v[26:29]
	v_mfma_f32_16x16x32_bf16 v[10:13], v[114:117], v[186:189], v[10:13]
	v_mfma_f32_16x16x32_bf16 v[10:13], v[122:125], v[190:193], v[10:13]
	v_mfma_f32_16x16x32_bf16 v[14:17], v[98:101], v[186:189], v[14:17]
	v_mfma_f32_16x16x32_bf16 v[14:17], v[102:105], v[190:193], v[14:17]
	v_mfma_f32_16x16x32_bf16 v[54:57], v[130:133], v[162:165], v[54:57]
	v_mfma_f32_16x16x32_bf16 v[54:57], v[138:141], v[166:169], v[54:57]
	v_mfma_f32_16x16x32_bf16 v[50:53], v[146:149], v[162:165], v[50:53]
	v_mfma_f32_16x16x32_bf16 v[50:53], v[154:157], v[166:169], v[50:53]
	v_mfma_f32_16x16x32_bf16 v[34:37], v[146:149], v[170:173], v[34:37]
	v_mfma_f32_16x16x32_bf16 v[34:37], v[154:157], v[174:177], v[34:37]
	v_mfma_f32_16x16x32_bf16 v[38:41], v[130:133], v[170:173], v[38:41]
	v_mfma_f32_16x16x32_bf16 v[38:41], v[138:141], v[174:177], v[38:41]
	v_mfma_f32_16x16x32_bf16 v[22:25], v[130:133], v[178:181], v[22:25]
	v_mfma_f32_16x16x32_bf16 v[22:25], v[138:141], v[182:185], v[22:25]
	v_mfma_f32_16x16x32_bf16 v[18:21], v[146:149], v[178:181], v[18:21]
	v_mfma_f32_16x16x32_bf16 v[18:21], v[154:157], v[182:185], v[18:21]
	v_mfma_f32_16x16x32_bf16 v[2:5], v[146:149], v[186:189], v[2:5]
	v_mfma_f32_16x16x32_bf16 v[2:5], v[154:157], v[190:193], v[2:5]
	v_mfma_f32_16x16x32_bf16 v[6:9], v[130:133], v[186:189], v[6:9]
	v_mfma_f32_16x16x32_bf16 v[6:9], v[138:141], v[190:193], v[6:9]
	s_barrier
	s_add_u32 s6, s6, s98
	s_addc_u32 s7, s7, 0
	s_add_u32 s6, s6, s98
	s_addc_u32 s7, s7, 0
	s_add_u32 s67, s67, s98
	s_addc_u32 s85, s85, 0
	s_add_u32 s67, s67, s98
	s_addc_u32 s85, s85, 0
	s_cmp_ge_u32 vcc_lo, s69
	s_mov_b32 s8, vcc_lo
	s_cbranch_scc0 .LBB0_175
	s_branch .Lpeelx175

; #define PG8_STAGE(bufoff, gbase, voff) do { _Pragma("unroll") for (int _i = 0; _i < 2; ++_i) \
;         __builtin_amdgcn_global_load_lds((const unsigned*)((const char*)(gbase) + (voff)[_i]), (PG8_LAS unsigned*)(lds + (bufoff) + ldsw + _i * 8192), 16, 0, 0); } while (0)
; #define PG8_LDA(dst, b, h) do { _Pragma("unroll") for (int m = 0; m < 4; ++m) _Pragma("unroll") for (int k = 0; k < 2; ++k) dst[m][k] = *(const PG8_LAS bf16x8*)(lds + PG8_SA(b, h) + aoff + m * 2048 + k * 1024); } while (0)
; #define PG8_LDB(dst, b, h) do { _Pragma("unroll") for (int n = 0; n < 2; ++n) _Pragma("unroll") for (int k = 0; k < 2; ++k) dst[n][k] = *(const PG8_LAS bf16x8*)(lds + PG8_SB(b, h) + boff + n * 2048 + k * 1024); } while (0)
; #define PG8_MMA(ai, bj, At, Bt) do { __builtin_amdgcn_s_setprio(1); _Pragma("unroll") for (int m = 0; m < 4; ++m) _Pragma("unroll") for (int n = 0; n < 2; ++n) _Pragma("unroll") for (int k = 0; k < 2; ++k) \
;         acc[ai][bj][m][n] = mma16<Epi::I8>(Bt[n][k], At[m][k], acc[ai][bj][m][n]); __builtin_amdgcn_s_setprio(0); } while (0)
; #define PG8_WAIT_V(n) asm volatile("s_waitcnt vmcnt(" #n ")" ::: "memory")
; #define PG8_WAIT_L(n) asm volatile("s_waitcnt lgkmcnt(" #n ")" ::: "memory")
; #define PG8_BAR __builtin_amdgcn_s_barrier()
; template <class Epi, class Sched, bool ALIGN_EPI = false, bool SP2 = false>
; __device__ __forceinline__ void gemm_phase(PG8_LAS unsigned char* lds, const Gemm g, const Sched& S, const Epi& E) {
;     ...
;             const bool last = (t == nt - 2);
;             const char* a1 = cA + (size_t)(t + 1) * kstep;
;             const char* a2 = last ? nA : cA + (size_t)(t + 2) * kstep; const char* b2 = last ? nB : cB + (size_t)(t + 2) * kstep;
;             const char* a3 = a2 + kstep; const char* b3 = b2 + kstep;
;             if (last && has_next) S.a_ready(nxt);
;             if constexpr (SP2) {
;             PG8_LDB(B0, 0, 0); PG8_LDB(B1, 0, 1); PG8_SCHED; PG8_LDA(At, 0, 0); PG8_STAGE(PG8_SA(1, 1), a1 + hstep, voffA);
;             PG8_WAIT_V(8); PG8_WAIT_L(0); PG8_BAR; PG8_MMA(0, 0, At, B0); PG8_MMA(0, 1, At, B1); PG8_BAR; PG8_SCHED;
;             PG8_LDA(At, 0, 1); PG8_STAGE(PG8_SB(0, 0), b2, voffB); PG8_STAGE(PG8_SB(0, 1), b2 + hstep, voffB); PG8_STAGE(PG8_SA(0, 0), a2, voffA);
;             PG8_WAIT_V(8); PG8_WAIT_L(0); PG8_BAR; PG8_MMA(1, 0, At, B0); PG8_MMA(1, 1, At, B1); PG8_BAR; PG8_SCHED;
.Lpeel327:
	s_add_u32 s68, s8, 0x100
	s_addc_u32 s69, s9, 0
	s_add_i32 s84, 0, 0x10000
	s_cmp_eq_u32 s4, 28
	s_cselect_b32 vcc_hi, s1, s69
	s_cselect_b32 vcc_lo, s5, s68
	v_add_u32_e32 v0, s84, v188
	s_cselect_b32 s71, s7, s96
	s_cselect_b32 s70, s85, s97
	s_add_i32 s10, 0, 0x14000
	ds_read_b128 v[52:55], v0
	ds_read_b128 v[56:59], v0 offset:1024
	ds_read_b128 v[76:79], v0 offset:2048
	ds_read_b128 v[80:83], v0 offset:3072
	v_add_u32_e32 v0, s10, v188
	ds_read_b128 v[116:119], v0
	ds_read_b128 v[120:123], v0 offset:1024
	ds_read_b128 v[168:171], v0 offset:2048
	ds_read_b128 v[172:175], v0 offset:3072
	v_lshl_add_u64 v[2:3], s[8:9], 0, v[164:165]
	s_add_i32 m0, s58, 0xc000
	ds_read_b128 v[176:179], v189
	ds_read_b128 v[180:183], v189 offset:1024
	ds_read_b128 v[190:193], v189 offset:2048
	ds_read_b128 v[194:197], v189 offset:3072
	ds_read_b128 v[198:201], v189 offset:4096
	ds_read_b128 v[210:213], v189 offset:5120
	ds_read_b128 v[214:217], v189 offset:6144
	ds_read_b128 v[218:221], v189 offset:7168
	global_load_lds_dwordx4 v[2:3], off
	v_lshl_add_u64 v[2:3], s[8:9], 0, v[166:167]
	s_add_i32 m0, s58, 0xe000
	s_nop 0
	global_load_lds_dwordx4 v[2:3], off
	s_waitcnt lgkmcnt(0)
	s_barrier
	s_waitcnt lgkmcnt(0)
	v_mfma_f32_16x16x32_bf16 v[152:155], v[52:55], v[176:179], 0
	v_mfma_f32_16x16x32_bf16 v[152:155], v[56:59], v[180:183], v[152:155]
	v_mfma_f32_16x16x32_bf16 v[144:147], v[76:79], v[176:179], 0
	v_mfma_f32_16x16x32_bf16 v[144:147], v[80:83], v[180:183], v[144:147]
	v_mfma_f32_16x16x32_bf16 v[140:143], v[76:79], v[190:193], 0
	v_mfma_f32_16x16x32_bf16 v[140:143], v[80:83], v[194:197], v[140:143]
	v_mfma_f32_16x16x32_bf16 v[148:151], v[52:55], v[190:193], 0
	v_mfma_f32_16x16x32_bf16 v[148:151], v[56:59], v[194:197], v[148:151]
	v_mfma_f32_16x16x32_bf16 v[136:139], v[52:55], v[198:201], 0
	v_mfma_f32_16x16x32_bf16 v[136:139], v[56:59], v[210:213], v[136:139]
	v_mfma_f32_16x16x32_bf16 v[132:135], v[76:79], v[198:201], 0
	v_mfma_f32_16x16x32_bf16 v[132:135], v[80:83], v[210:213], v[132:135]
	v_mfma_f32_16x16x32_bf16 v[124:127], v[76:79], v[214:217], 0
	v_mfma_f32_16x16x32_bf16 v[124:127], v[80:83], v[218:221], v[124:127]
	v_mfma_f32_16x16x32_bf16 v[128:131], v[52:55], v[214:217], 0
	v_mfma_f32_16x16x32_bf16 v[128:131], v[56:59], v[218:221], v[128:131]
	v_mfma_f32_16x16x32_bf16 v[112:115], v[116:119], v[176:179], 0
	v_mfma_f32_16x16x32_bf16 v[112:115], v[120:123], v[180:183], v[112:115]
	v_mfma_f32_16x16x32_bf16 v[104:107], v[168:171], v[176:179], 0
	v_mfma_f32_16x16x32_bf16 v[104:107], v[172:175], v[180:183], v[104:107]
	v_mfma_f32_16x16x32_bf16 v[100:103], v[168:171], v[190:193], 0
	v_mfma_f32_16x16x32_bf16 v[100:103], v[172:175], v[194:197], v[100:103]
	v_mfma_f32_16x16x32_bf16 v[108:111], v[116:119], v[190:193], 0
	v_mfma_f32_16x16x32_bf16 v[108:111], v[120:123], v[194:197], v[108:111]
	v_mfma_f32_16x16x32_bf16 v[96:99], v[116:119], v[198:201], 0
	v_mfma_f32_16x16x32_bf16 v[96:99], v[120:123], v[210:213], v[96:99]
	v_mfma_f32_16x16x32_bf16 v[92:95], v[168:171], v[198:201], 0
	v_mfma_f32_16x16x32_bf16 v[92:95], v[172:175], v[210:213], v[92:95]
	v_mfma_f32_16x16x32_bf16 v[84:87], v[168:171], v[214:217], 0
	v_mfma_f32_16x16x32_bf16 v[84:87], v[172:175], v[218:221], v[84:87]
	v_mfma_f32_16x16x32_bf16 v[88:91], v[116:119], v[214:217], 0
	v_mfma_f32_16x16x32_bf16 v[88:91], v[120:123], v[218:221], v[88:91]
	s_barrier
	s_add_i32 s8, s84, s80
	v_lshl_add_u64 v[184:185], s[70:71], 0, v[158:159]
	s_mov_b32 m0, s8
	ds_read_b128 v[176:179], v189 offset:16384
	ds_read_b128 v[180:183], v189 offset:17408
	ds_read_b128 v[190:193], v189 offset:18432
	ds_read_b128 v[194:197], v189 offset:19456
	ds_read_b128 v[198:201], v189 offset:20480
	ds_read_b128 v[210:213], v189 offset:21504
	ds_read_b128 v[214:217], v189 offset:22528
	ds_read_b128 v[218:221], v189 offset:23552
	global_load_lds_dwordx4 v[184:185], off
	s_add_i32 m0, s8, 0x2000
	s_add_u32 s8, s70, 0x80000
	v_lshl_add_u64 v[206:207], s[70:71], 0, v[162:163]
	s_addc_u32 s9, s71, 0
	s_add_i32 s10, s10, s80
	global_load_lds_dwordx4 v[206:207], off
	v_lshl_add_u64 v[2:3], s[8:9], 0, v[158:159]
	s_mov_b32 m0, s10
	v_lshl_add_u64 v[222:223], vcc, 0, v[156:157]
	global_load_lds_dwordx4 v[2:3], off
	v_lshl_add_u64 v[2:3], s[8:9], 0, v[162:163]
	s_add_i32 m0, s10, 0x2000
	v_lshl_add_u64 v[224:225], vcc, 0, v[160:161]
	global_load_lds_dwordx4 v[2:3], off
	s_mov_b32 m0, s58
	s_nop 0
	global_load_lds_dwordx4 v[222:223], off
	s_mov_b32 m0, s12
	s_nop 0
	global_load_lds_dwordx4 v[224:225], off
	s_waitcnt lgkmcnt(0)
	s_barrier
	s_waitcnt lgkmcnt(0)
	v_mfma_f32_16x16x32_bf16 v[72:75], v[52:55], v[176:179], 0
	v_mfma_f32_16x16x32_bf16 v[72:75], v[56:59], v[180:183], v[72:75]
	v_mfma_f32_16x16x32_bf16 v[64:67], v[76:79], v[176:179], 0
	v_mfma_f32_16x16x32_bf16 v[64:67], v[80:83], v[180:183], v[64:67]
	v_mfma_f32_16x16x32_bf16 v[60:63], v[76:79], v[190:193], 0
	v_mfma_f32_16x16x32_bf16 v[60:63], v[80:83], v[194:197], v[60:63]
	v_mfma_f32_16x16x32_bf16 v[68:71], v[52:55], v[190:193], 0
	v_mfma_f32_16x16x32_bf16 v[68:71], v[56:59], v[194:197], v[68:71]
	v_mfma_f32_16x16x32_bf16 v[48:51], v[52:55], v[198:201], 0
	v_mfma_f32_16x16x32_bf16 v[48:51], v[56:59], v[210:213], v[48:51]
	v_mfma_f32_16x16x32_bf16 v[44:47], v[76:79], v[198:201], 0
	v_mfma_f32_16x16x32_bf16 v[44:47], v[80:83], v[210:213], v[44:47]
	v_mfma_f32_16x16x32_bf16 v[36:39], v[76:79], v[214:217], 0
	v_mfma_f32_16x16x32_bf16 v[36:39], v[80:83], v[218:221], v[36:39]
	v_mfma_f32_16x16x32_bf16 v[40:43], v[52:55], v[214:217], 0
	v_mfma_f32_16x16x32_bf16 v[40:43], v[56:59], v[218:221], v[40:43]
	v_mfma_f32_16x16x32_bf16 v[32:35], v[116:119], v[176:179], 0
	v_mfma_f32_16x16x32_bf16 v[32:35], v[120:123], v[180:183], v[32:35]
	v_mfma_f32_16x16x32_bf16 v[24:27], v[168:171], v[176:179], 0
	v_mfma_f32_16x16x32_bf16 v[24:27], v[172:175], v[180:183], v[24:27]
	v_mfma_f32_16x16x32_bf16 v[20:23], v[168:171], v[190:193], 0
	v_mfma_f32_16x16x32_bf16 v[20:23], v[172:175], v[194:197], v[20:23]
	v_mfma_f32_16x16x32_bf16 v[28:31], v[116:119], v[190:193], 0
	v_mfma_f32_16x16x32_bf16 v[28:31], v[120:123], v[194:197], v[28:31]
	v_mfma_f32_16x16x32_bf16 v[16:19], v[116:119], v[198:201], 0
	v_mfma_f32_16x16x32_bf16 v[16:19], v[120:123], v[210:213], v[16:19]
	v_mfma_f32_16x16x32_bf16 v[12:15], v[168:171], v[198:201], 0
	v_mfma_f32_16x16x32_bf16 v[12:15], v[172:175], v[210:213], v[12:15]
	v_mfma_f32_16x16x32_bf16 v[2:5], v[168:171], v[214:217], 0
	v_mfma_f32_16x16x32_bf16 v[2:5], v[172:175], v[218:221], v[2:5]
	v_mfma_f32_16x16x32_bf16 v[8:11], v[116:119], v[214:217], 0
	v_mfma_f32_16x16x32_bf16 v[8:11], v[120:123], v[218:221], v[8:11]
	s_barrier
; #define PG8_STAGE(bufoff, gbase, voff) do { _Pragma("unroll") for (int _i = 0; _i < 2; ++_i) \
;         __builtin_amdgcn_global_load_lds((const unsigned*)((const char*)(gbase) + (voff)[_i]), (PG8_LAS unsigned*)(lds + (bufoff) + ldsw + _i * 8192), 16, 0, 0); } while (0)
; #define PG8_LDA(dst, b, h) do { _Pragma("unroll") for (int m = 0; m < 4; ++m) _Pragma("unroll") for (int k = 0; k < 2; ++k) dst[m][k] = *(const PG8_LAS bf16x8*)(lds + PG8_SA(b, h) + aoff + m * 2048 + k * 1024); } while (0)
; #define PG8_LDB(dst, b, h) do { _Pragma("unroll") for (int n = 0; n < 2; ++n) _Pragma("unroll") for (int k = 0; k < 2; ++k) dst[n][k] = *(const PG8_LAS bf16x8*)(lds + PG8_SB(b, h) + boff + n * 2048 + k * 1024); } while (0)
; #define PG8_MMA(ai, bj, At, Bt) do { __builtin_amdgcn_s_setprio(1); _Pragma("unroll") for (int m = 0; m < 4; ++m) _Pragma("unroll") for (int n = 0; n < 2; ++n) _Pragma("unroll") for (int k = 0; k < 2; ++k) \
;         acc[ai][bj][m][n] = mma16<Epi::I8>(Bt[n][k], At[m][k], acc[ai][bj][m][n]); __builtin_amdgcn_s_setprio(0); } while (0)
; #define PG8_WAIT_V(n) asm volatile("s_waitcnt vmcnt(" #n ")" ::: "memory")
; #define PG8_WAIT_L(n) asm volatile("s_waitcnt lgkmcnt(" #n ")" ::: "memory")
; #define PG8_BAR __builtin_amdgcn_s_barrier()
; #define PG8_SCHED __builtin_amdgcn_sched_barrier(0)
; template <class Epi, class Sched, bool ALIGN_EPI = false, bool SP2 = false>
; __device__ __forceinline__ void gemm_phase(PG8_LAS unsigned char* lds, const Gemm g, const Sched& S, const Epi& E) {
;     ...
;             PG8_LDB(B0, 1, 0); PG8_LDB(B1, 1, 1); PG8_SCHED; PG8_LDA(At, 1, 0); PG8_STAGE(PG8_SA(0, 1), a2 + hstep, voffA);
;             PG8_WAIT_V(8); PG8_WAIT_L(0); PG8_BAR; PG8_MMA(0, 0, At, B0); PG8_MMA(0, 1, At, B1); PG8_BAR; PG8_SCHED;
;             PG8_LDA(At, 1, 1); PG8_STAGE(PG8_SB(1, 0), b3, voffB); PG8_STAGE(PG8_SB(1, 1), b3 + hstep, voffB); PG8_STAGE(PG8_SA(1, 0), a3, voffA);
;             PG8_WAIT_V(8); PG8_WAIT_L(0); PG8_BAR; PG8_MMA(1, 0, At, B0); PG8_MMA(1, 1, At, B1); PG8_BAR; PG8_SCHED;
	s_add_i32 s10, 0, 0x18000
	v_add_u32_e32 v0, s10, v188
	s_add_i32 s11, 0, 0x1c000
	ds_read_b128 v[52:55], v0
	ds_read_b128 v[56:59], v0 offset:1024
	ds_read_b128 v[76:79], v0 offset:2048
	ds_read_b128 v[80:83], v0 offset:3072
	v_add_u32_e32 v0, s11, v188
	ds_read_b128 v[116:119], v0
	ds_read_b128 v[120:123], v0 offset:1024
	ds_read_b128 v[168:171], v0 offset:2048
	ds_read_b128 v[172:175], v0 offset:3072
	s_add_u32 s8, vcc_lo, 0x80000
	s_addc_u32 s9, vcc_hi, 0
	s_mov_b32 m0, s13
	v_lshl_add_u64 v[6:7], s[8:9], 0, v[156:157]
	ds_read_b128 v[176:179], v189 offset:32768
	ds_read_b128 v[180:183], v189 offset:33792
	ds_read_b128 v[190:193], v189 offset:34816
	ds_read_b128 v[194:197], v189 offset:35840
	ds_read_b128 v[198:201], v189 offset:36864
	ds_read_b128 v[210:213], v189 offset:37888
	ds_read_b128 v[214:217], v189 offset:38912
	ds_read_b128 v[218:221], v189 offset:39936
	global_load_lds_dwordx4 v[6:7], off
	v_lshl_add_u64 v[6:7], s[8:9], 0, v[160:161]
	s_mov_b32 m0, s66
	s_nop 0
	global_load_lds_dwordx4 v[6:7], off
	s_waitcnt vmcnt(8)
	s_waitcnt lgkmcnt(0)
	s_barrier
	s_waitcnt lgkmcnt(0)
	v_mfma_f32_16x16x32_bf16 v[152:155], v[52:55], v[176:179], v[152:155]
	v_mfma_f32_16x16x32_bf16 v[152:155], v[56:59], v[180:183], v[152:155]
	v_mfma_f32_16x16x32_bf16 v[144:147], v[76:79], v[176:179], v[144:147]
	v_mfma_f32_16x16x32_bf16 v[144:147], v[80:83], v[180:183], v[144:147]
	v_mfma_f32_16x16x32_bf16 v[140:143], v[76:79], v[190:193], v[140:143]
	v_mfma_f32_16x16x32_bf16 v[140:143], v[80:83], v[194:197], v[140:143]
	v_mfma_f32_16x16x32_bf16 v[148:151], v[52:55], v[190:193], v[148:151]
	v_mfma_f32_16x16x32_bf16 v[148:151], v[56:59], v[194:197], v[148:151]
	v_mfma_f32_16x16x32_bf16 v[136:139], v[52:55], v[198:201], v[136:139]
	v_mfma_f32_16x16x32_bf16 v[136:139], v[56:59], v[210:213], v[136:139]
	v_mfma_f32_16x16x32_bf16 v[132:135], v[76:79], v[198:201], v[132:135]
	v_mfma_f32_16x16x32_bf16 v[132:135], v[80:83], v[210:213], v[132:135]
	v_mfma_f32_16x16x32_bf16 v[124:127], v[76:79], v[214:217], v[124:127]
	v_mfma_f32_16x16x32_bf16 v[124:127], v[80:83], v[218:221], v[124:127]
	v_mfma_f32_16x16x32_bf16 v[128:131], v[52:55], v[214:217], v[128:131]
	v_mfma_f32_16x16x32_bf16 v[128:131], v[56:59], v[218:221], v[128:131]
	v_mfma_f32_16x16x32_bf16 v[112:115], v[116:119], v[176:179], v[112:115]
	v_mfma_f32_16x16x32_bf16 v[112:115], v[120:123], v[180:183], v[112:115]
	v_mfma_f32_16x16x32_bf16 v[104:107], v[168:171], v[176:179], v[104:107]
	v_mfma_f32_16x16x32_bf16 v[104:107], v[172:175], v[180:183], v[104:107]
	v_mfma_f32_16x16x32_bf16 v[100:103], v[168:171], v[190:193], v[100:103]
	v_mfma_f32_16x16x32_bf16 v[100:103], v[172:175], v[194:197], v[100:103]
	v_mfma_f32_16x16x32_bf16 v[108:111], v[116:119], v[190:193], v[108:111]
	v_mfma_f32_16x16x32_bf16 v[108:111], v[120:123], v[194:197], v[108:111]
	v_mfma_f32_16x16x32_bf16 v[96:99], v[116:119], v[198:201], v[96:99]
	v_mfma_f32_16x16x32_bf16 v[96:99], v[120:123], v[210:213], v[96:99]
	v_mfma_f32_16x16x32_bf16 v[92:95], v[168:171], v[198:201], v[92:95]
	v_mfma_f32_16x16x32_bf16 v[92:95], v[172:175], v[210:213], v[92:95]
	v_mfma_f32_16x16x32_bf16 v[84:87], v[168:171], v[214:217], v[84:87]
	v_mfma_f32_16x16x32_bf16 v[84:87], v[172:175], v[218:221], v[84:87]
	v_mfma_f32_16x16x32_bf16 v[88:91], v[116:119], v[214:217], v[88:91]
	v_mfma_f32_16x16x32_bf16 v[88:91], v[120:123], v[218:221], v[88:91]
	s_barrier
	s_add_i32 s8, s10, s80
	v_lshl_add_u64 v[6:7], v[184:185], 0, s[92:93]
	s_mov_b32 m0, s8
	ds_read_b128 v[176:179], v189 offset:49152
	ds_read_b128 v[180:183], v189 offset:50176
	ds_read_b128 v[190:193], v189 offset:51200
	ds_read_b128 v[194:197], v189 offset:52224
	ds_read_b128 v[198:201], v189 offset:53248
	ds_read_b128 v[210:213], v189 offset:54272
	ds_read_b128 v[214:217], v189 offset:55296
	ds_read_b128 v[218:221], v189 offset:56320
	global_load_lds_dwordx4 v[6:7], off
	s_add_i32 m0, s8, 0x2000
	s_add_u32 s8, s70, 0x80080
	v_lshl_add_u64 v[6:7], v[206:207], 0, s[92:93]
	s_addc_u32 s9, s71, 0
	s_add_i32 s10, s11, s80
	global_load_lds_dwordx4 v[6:7], off
	v_lshl_add_u64 v[6:7], s[8:9], 0, v[158:159]
	s_mov_b32 m0, s10
	s_nop 0
	global_load_lds_dwordx4 v[6:7], off
	v_lshl_add_u64 v[6:7], s[8:9], 0, v[162:163]
	s_add_i32 m0, s10, 0x2000
	s_nop 0
	global_load_lds_dwordx4 v[6:7], off
	v_lshl_add_u64 v[6:7], v[222:223], 0, s[92:93]
	s_mov_b32 m0, s67
	s_nop 0
	global_load_lds_dwordx4 v[6:7], off
	v_lshl_add_u64 v[6:7], v[224:225], 0, s[92:93]
	s_mov_b32 m0, s81
	s_nop 0
	global_load_lds_dwordx4 v[6:7], off
	s_waitcnt vmcnt(8)
	s_waitcnt lgkmcnt(0)
	s_barrier
	s_waitcnt lgkmcnt(0)
	v_mfma_f32_16x16x32_bf16 v[72:75], v[52:55], v[176:179], v[72:75]
	v_mfma_f32_16x16x32_bf16 v[72:75], v[56:59], v[180:183], v[72:75]
	v_mfma_f32_16x16x32_bf16 v[64:67], v[76:79], v[176:179], v[64:67]
	v_mfma_f32_16x16x32_bf16 v[64:67], v[80:83], v[180:183], v[64:67]
	v_mfma_f32_16x16x32_bf16 v[60:63], v[76:79], v[190:193], v[60:63]
	v_mfma_f32_16x16x32_bf16 v[60:63], v[80:83], v[194:197], v[60:63]
	v_mfma_f32_16x16x32_bf16 v[68:71], v[52:55], v[190:193], v[68:71]
	v_mfma_f32_16x16x32_bf16 v[68:71], v[56:59], v[194:197], v[68:71]
	v_mfma_f32_16x16x32_bf16 v[48:51], v[52:55], v[198:201], v[48:51]
	v_mfma_f32_16x16x32_bf16 v[48:51], v[56:59], v[210:213], v[48:51]
	v_mfma_f32_16x16x32_bf16 v[44:47], v[76:79], v[198:201], v[44:47]
	v_mfma_f32_16x16x32_bf16 v[44:47], v[80:83], v[210:213], v[44:47]
	v_mfma_f32_16x16x32_bf16 v[36:39], v[76:79], v[214:217], v[36:39]
	v_mfma_f32_16x16x32_bf16 v[36:39], v[80:83], v[218:221], v[36:39]
	v_mfma_f32_16x16x32_bf16 v[40:43], v[52:55], v[214:217], v[40:43]
	v_mfma_f32_16x16x32_bf16 v[40:43], v[56:59], v[218:221], v[40:43]
	v_mfma_f32_16x16x32_bf16 v[32:35], v[116:119], v[176:179], v[32:35]
	v_mfma_f32_16x16x32_bf16 v[32:35], v[120:123], v[180:183], v[32:35]
	v_mfma_f32_16x16x32_bf16 v[24:27], v[168:171], v[176:179], v[24:27]
	v_mfma_f32_16x16x32_bf16 v[24:27], v[172:175], v[180:183], v[24:27]
	v_mfma_f32_16x16x32_bf16 v[20:23], v[168:171], v[190:193], v[20:23]
	v_mfma_f32_16x16x32_bf16 v[20:23], v[172:175], v[194:197], v[20:23]
	v_mfma_f32_16x16x32_bf16 v[28:31], v[116:119], v[190:193], v[28:31]
	v_mfma_f32_16x16x32_bf16 v[28:31], v[120:123], v[194:197], v[28:31]
	v_mfma_f32_16x16x32_bf16 v[16:19], v[116:119], v[198:201], v[16:19]
	v_mfma_f32_16x16x32_bf16 v[16:19], v[120:123], v[210:213], v[16:19]
	v_mfma_f32_16x16x32_bf16 v[12:15], v[168:171], v[198:201], v[12:15]
	v_mfma_f32_16x16x32_bf16 v[12:15], v[172:175], v[210:213], v[12:15]
	v_mfma_f32_16x16x32_bf16 v[2:5], v[168:171], v[214:217], v[2:5]
	v_mfma_f32_16x16x32_bf16 v[6:9], v[116:119], v[214:217], v[8:11]
	v_mfma_f32_16x16x32_bf16 v[8:11], v[120:123], v[218:221], v[6:9]
	v_mfma_f32_16x16x32_bf16 v[4:7], v[172:175], v[218:221], v[2:5]
	s_barrier
	s_add_i32 s4, s4, 2
	s_add_u32 s97, s97, 0x100
	s_addc_u32 s96, s96, 0
	s_cmp_gt_u32 s4, 29
	s_mov_b64 s[8:9], s[68:69]
	s_cbranch_scc0 .LBB0_327
	s_branch .Lpeelx327

; #define PG8_STAGE(bufoff, gbase, voff) do { _Pragma("unroll") for (int _i = 0; _i < 2; ++_i) \
;         __builtin_amdgcn_global_load_lds((const unsigned*)((const char*)(gbase) + (voff)[_i]), (PG8_LAS unsigned*)(lds + (bufoff) + ldsw + _i * 8192), 16, 0, 0); } while (0)
; #define PG8_LDA(dst, b, h) do { _Pragma("unroll") for (int m = 0; m < 4; ++m) _Pragma("unroll") for (int k = 0; k < 2; ++k) dst[m][k] = *(const PG8_LAS bf16x8*)(lds + PG8_SA(b, h) + aoff + m * 2048 + k * 1024); } while (0)
; #define PG8_LDB(dst, b, h) do { _Pragma("unroll") for (int n = 0; n < 2; ++n) _Pragma("unroll") for (int k = 0; k < 2; ++k) dst[n][k] = *(const PG8_LAS bf16x8*)(lds + PG8_SB(b, h) + boff + n * 2048 + k * 1024); } while (0)
; #define PG8_MMA(ai, bj, At, Bt) do { __builtin_amdgcn_s_setprio(1); _Pragma("unroll") for (int m = 0; m < 4; ++m) _Pragma("unroll") for (int n = 0; n < 2; ++n) _Pragma("unroll") for (int k = 0; k < 2; ++k) \
;         acc[ai][bj][m][n] = mma16<Epi::I8>(Bt[n][k], At[m][k], acc[ai][bj][m][n]); __builtin_amdgcn_s_setprio(0); } while (0)
; #define PG8_WAIT_V(n) asm volatile("s_waitcnt vmcnt(" #n ")" ::: "memory")
; #define PG8_WAIT_L(n) asm volatile("s_waitcnt lgkmcnt(" #n ")" ::: "memory")
; #define PG8_BAR __builtin_amdgcn_s_barrier()
; #define PG8_SCHED __builtin_amdgcn_sched_barrier(0)
; template <class Epi, class Sched, bool ALIGN_EPI = false, bool SP2 = false>
; __device__ __forceinline__ void gemm_phase(PG8_LAS unsigned char* lds, const Gemm g, const Sched& S, const Epi& E) {
;     ...
;             const char* a1 = cA + (size_t)(t + 1) * kstep;
;             const char* a2 = last ? nA : cA + (size_t)(t + 2) * kstep; const char* b2 = last ? nB : cB + (size_t)(t + 2) * kstep;
;             const char* a3 = a2 + kstep; const char* b3 = b2 + kstep;
;             if (last && has_next) S.a_ready(nxt);
;             if constexpr (SP2) {
;             PG8_LDB(B0, 0, 0); PG8_LDB(B1, 0, 1); PG8_SCHED; PG8_LDA(At, 0, 0); PG8_STAGE(PG8_SA(1, 1), a1 + hstep, voffA);
;             PG8_WAIT_V(8); PG8_WAIT_L(0); PG8_BAR; PG8_MMA(0, 0, At, B0); PG8_MMA(0, 1, At, B1); PG8_BAR; PG8_SCHED;
;             PG8_LDA(At, 0, 1); PG8_STAGE(PG8_SB(0, 0), b2, voffB); PG8_STAGE(PG8_SB(0, 1), b2 + hstep, voffB); PG8_STAGE(PG8_SA(0, 0), a2, voffA);
;             PG8_WAIT_V(8); PG8_WAIT_L(0); PG8_BAR; PG8_MMA(1, 0, At, B0); PG8_MMA(1, 1, At, B1); PG8_BAR; PG8_SCHED;
.Lpeel385:
	s_add_u32 s70, s8, 0x100
	s_addc_u32 s71, s9, 0
	s_add_i32 s84, 0, 0x10000
	s_cmp_eq_u32 s5, 12
	s_cselect_b32 vcc_hi, s1, s71
	s_cselect_b32 vcc_lo, s7, s70
	v_add_u32_e32 v0, s84, v214
	s_cselect_b32 s83, s69, s68
	s_cselect_b32 s82, s81, s85
	s_add_i32 s10, 0, 0x14000
	ds_read_b128 v[44:47], v0
	ds_read_b128 v[52:55], v0 offset:1024
	ds_read_b128 v[60:63], v0 offset:2048
	ds_read_b128 v[64:67], v0 offset:3072
	v_add_u32_e32 v0, s10, v214
	ds_read_b128 v[84:87], v0
	ds_read_b128 v[88:91], v0 offset:1024
	ds_read_b128 v[92:95], v0 offset:2048
	ds_read_b128 v[100:103], v0 offset:3072
	v_lshl_add_u64 v[2:3], s[8:9], 0, v[184:185]
	s_add_i32 m0, s13, 0xc000
	ds_read_b128 v[124:127], v215
	ds_read_b128 v[128:131], v215 offset:1024
	ds_read_b128 v[140:143], v215 offset:2048
	ds_read_b128 v[188:191], v215 offset:3072
	ds_read_b128 v[192:195], v215 offset:4096
	ds_read_b128 v[196:199], v215 offset:5120
	ds_read_b128 v[216:219], v215 offset:6144
	ds_read_b128 v[220:223], v215 offset:7168
	global_load_lds_dwordx4 v[2:3], off
	v_lshl_add_u64 v[2:3], s[8:9], 0, v[186:187]
	s_add_i32 m0, s13, 0xe000
	s_nop 0
	global_load_lds_dwordx4 v[2:3], off
	s_waitcnt lgkmcnt(0)
	s_barrier
	s_waitcnt lgkmcnt(0)
	v_mfma_i32_16x16x64_i8 v[172:175], v[44:47], v[124:127], 0
	v_mfma_i32_16x16x64_i8 v[172:175], v[52:55], v[128:131], v[172:175]
	v_mfma_i32_16x16x64_i8 v[164:167], v[64:67], v[128:131], 0
	v_mfma_i32_16x16x64_i8 v[164:167], v[60:63], v[124:127], v[164:167]
	v_mfma_i32_16x16x64_i8 v[160:163], v[60:63], v[140:143], 0
	v_mfma_i32_16x16x64_i8 v[160:163], v[64:67], v[188:191], v[160:163]
	v_mfma_i32_16x16x64_i8 v[168:171], v[52:55], v[188:191], 0
	v_mfma_i32_16x16x64_i8 v[168:171], v[44:47], v[140:143], v[168:171]
	v_mfma_i32_16x16x64_i8 v[156:159], v[44:47], v[192:195], 0
	v_mfma_i32_16x16x64_i8 v[156:159], v[52:55], v[196:199], v[156:159]
	v_mfma_i32_16x16x64_i8 v[152:155], v[64:67], v[196:199], 0
	v_mfma_i32_16x16x64_i8 v[152:155], v[60:63], v[192:195], v[152:155]
	v_mfma_i32_16x16x64_i8 v[144:147], v[60:63], v[216:219], 0
	v_mfma_i32_16x16x64_i8 v[144:147], v[64:67], v[220:223], v[144:147]
	v_mfma_i32_16x16x64_i8 v[148:151], v[52:55], v[220:223], 0
	v_mfma_i32_16x16x64_i8 v[148:151], v[44:47], v[216:219], v[148:151]
	v_mfma_i32_16x16x64_i8 v[104:107], v[84:87], v[216:219], 0
	v_mfma_i32_16x16x64_i8 v[104:107], v[88:91], v[220:223], v[104:107]
	v_mfma_i32_16x16x64_i8 v[136:139], v[88:91], v[128:131], 0
	v_mfma_i32_16x16x64_i8 v[136:139], v[84:87], v[124:127], v[136:139]
	v_mfma_i32_16x16x64_i8 v[120:123], v[92:95], v[124:127], 0
	v_mfma_i32_16x16x64_i8 v[120:123], v[100:103], v[128:131], v[120:123]
	v_mfma_i32_16x16x64_i8 v[116:119], v[100:103], v[188:191], 0
	v_mfma_i32_16x16x64_i8 v[116:119], v[92:95], v[140:143], v[116:119]
	v_mfma_i32_16x16x64_i8 v[108:111], v[92:95], v[192:195], 0
	v_mfma_i32_16x16x64_i8 v[108:111], v[100:103], v[196:199], v[108:111]
	v_mfma_i32_16x16x64_i8 v[112:115], v[88:91], v[196:199], 0
	v_mfma_i32_16x16x64_i8 v[112:115], v[84:87], v[192:195], v[112:115]
	v_mfma_i32_16x16x64_i8 v[124:127], v[84:87], v[140:143], 0
	v_mfma_i32_16x16x64_i8 v[124:127], v[88:91], v[188:191], v[124:127]
	v_mfma_i32_16x16x64_i8 v[96:99], v[92:95], v[216:219], 0
	v_mfma_i32_16x16x64_i8 v[96:99], v[100:103], v[220:223], v[96:99]
	s_barrier
	s_add_i32 s8, s84, s12
	v_lshl_add_u64 v[200:201], s[82:83], 0, v[178:179]
	s_mov_b32 m0, s8
	ds_read_b128 v[128:131], v215 offset:16384
	ds_read_b128 v[132:135], v215 offset:17408
	ds_read_b128 v[140:143], v215 offset:18432
	ds_read_b128 v[188:191], v215 offset:19456
	ds_read_b128 v[192:195], v215 offset:20480
	ds_read_b128 v[196:199], v215 offset:21504
	ds_read_b128 v[216:219], v215 offset:22528
	ds_read_b128 v[220:223], v215 offset:23552
	global_load_lds_dwordx4 v[200:201], off
	s_add_i32 m0, s8, 0x2000
	s_add_u32 s8, s82, 0x40000
	v_lshl_add_u64 v[206:207], s[82:83], 0, v[182:183]
	s_addc_u32 s9, s83, 0
	s_add_i32 s10, s10, s12
	global_load_lds_dwordx4 v[206:207], off
	v_lshl_add_u64 v[2:3], s[8:9], 0, v[178:179]
	s_mov_b32 m0, s10
	v_lshl_add_u64 v[210:211], vcc, 0, v[176:177]
	global_load_lds_dwordx4 v[2:3], off
	v_lshl_add_u64 v[2:3], s[8:9], 0, v[182:183]
	s_add_i32 m0, s10, 0x2000
	v_lshl_add_u64 v[224:225], vcc, 0, v[180:181]
	global_load_lds_dwordx4 v[2:3], off
	s_mov_b32 m0, s13
	s_nop 0
	global_load_lds_dwordx4 v[210:211], off
	s_mov_b32 m0, s66
	s_nop 0
	global_load_lds_dwordx4 v[224:225], off
	s_waitcnt lgkmcnt(0)
	s_barrier
	s_waitcnt lgkmcnt(0)
	v_mfma_i32_16x16x64_i8 v[80:83], v[44:47], v[128:131], 0
	v_mfma_i32_16x16x64_i8 v[80:83], v[52:55], v[132:135], v[80:83]
	v_mfma_i32_16x16x64_i8 v[72:75], v[64:67], v[132:135], 0
	v_mfma_i32_16x16x64_i8 v[72:75], v[60:63], v[128:131], v[72:75]
	v_mfma_i32_16x16x64_i8 v[68:71], v[60:63], v[140:143], 0
	v_mfma_i32_16x16x64_i8 v[68:71], v[64:67], v[188:191], v[68:71]
	v_mfma_i32_16x16x64_i8 v[76:79], v[52:55], v[188:191], 0
	v_mfma_i32_16x16x64_i8 v[76:79], v[44:47], v[140:143], v[76:79]
	v_mfma_i32_16x16x64_i8 v[56:59], v[44:47], v[192:195], 0
	v_mfma_i32_16x16x64_i8 v[56:59], v[52:55], v[196:199], v[56:59]
	v_mfma_i32_16x16x64_i8 v[48:51], v[64:67], v[196:199], 0
	v_mfma_i32_16x16x64_i8 v[48:51], v[60:63], v[192:195], v[48:51]
	v_mfma_i32_16x16x64_i8 v[36:39], v[60:63], v[216:219], 0
	v_mfma_i32_16x16x64_i8 v[36:39], v[64:67], v[220:223], v[36:39]
	v_mfma_i32_16x16x64_i8 v[40:43], v[52:55], v[220:223], 0
	v_mfma_i32_16x16x64_i8 v[40:43], v[44:47], v[216:219], v[40:43]
	v_mfma_i32_16x16x64_i8 v[2:5], v[92:95], v[216:219], 0
	v_mfma_i32_16x16x64_i8 v[2:5], v[100:103], v[220:223], v[2:5]
	v_mfma_i32_16x16x64_i8 v[24:27], v[100:103], v[132:135], 0
	v_mfma_i32_16x16x64_i8 v[24:27], v[92:95], v[128:131], v[24:27]
	v_mfma_i32_16x16x64_i8 v[32:35], v[84:87], v[128:131], 0
	v_mfma_i32_16x16x64_i8 v[32:35], v[88:91], v[132:135], v[32:35]
	v_mfma_i32_16x16x64_i8 v[28:31], v[88:91], v[188:191], 0
	v_mfma_i32_16x16x64_i8 v[28:31], v[84:87], v[140:143], v[28:31]
	v_mfma_i32_16x16x64_i8 v[20:23], v[92:95], v[140:143], 0
	v_mfma_i32_16x16x64_i8 v[20:23], v[100:103], v[188:191], v[20:23]
	v_mfma_i32_16x16x64_i8 v[12:15], v[100:103], v[196:199], 0
	v_mfma_i32_16x16x64_i8 v[12:15], v[92:95], v[192:195], v[12:15]
	v_mfma_i32_16x16x64_i8 v[16:19], v[84:87], v[192:195], 0
	v_mfma_i32_16x16x64_i8 v[16:19], v[88:91], v[196:199], v[16:19]
	v_mfma_i32_16x16x64_i8 v[8:11], v[88:91], v[220:223], 0
	v_mfma_i32_16x16x64_i8 v[8:11], v[84:87], v[216:219], v[8:11]
	s_barrier
; #define PG8_STAGE(bufoff, gbase, voff) do { _Pragma("unroll") for (int _i = 0; _i < 2; ++_i) \
;         __builtin_amdgcn_global_load_lds((const unsigned*)((const char*)(gbase) + (voff)[_i]), (PG8_LAS unsigned*)(lds + (bufoff) + ldsw + _i * 8192), 16, 0, 0); } while (0)
; #define PG8_LDA(dst, b, h) do { _Pragma("unroll") for (int m = 0; m < 4; ++m) _Pragma("unroll") for (int k = 0; k < 2; ++k) dst[m][k] = *(const PG8_LAS bf16x8*)(lds + PG8_SA(b, h) + aoff + m * 2048 + k * 1024); } while (0)
; #define PG8_LDB(dst, b, h) do { _Pragma("unroll") for (int n = 0; n < 2; ++n) _Pragma("unroll") for (int k = 0; k < 2; ++k) dst[n][k] = *(const PG8_LAS bf16x8*)(lds + PG8_SB(b, h) + boff + n * 2048 + k * 1024); } while (0)
; #define PG8_MMA(ai, bj, At, Bt) do { __builtin_amdgcn_s_setprio(1); _Pragma("unroll") for (int m = 0; m < 4; ++m) _Pragma("unroll") for (int n = 0; n < 2; ++n) _Pragma("unroll") for (int k = 0; k < 2; ++k) \
;         acc[ai][bj][m][n] = mma16<Epi::I8>(Bt[n][k], At[m][k], acc[ai][bj][m][n]); __builtin_amdgcn_s_setprio(0); } while (0)
; #define PG8_WAIT_V(n) asm volatile("s_waitcnt vmcnt(" #n ")" ::: "memory")
; #define PG8_WAIT_L(n) asm volatile("s_waitcnt lgkmcnt(" #n ")" ::: "memory")
; #define PG8_BAR __builtin_amdgcn_s_barrier()
; #define PG8_SCHED __builtin_amdgcn_sched_barrier(0)
; template <class Epi, class Sched, bool ALIGN_EPI = false, bool SP2 = false>
; __device__ __forceinline__ void gemm_phase(PG8_LAS unsigned char* lds, const Gemm g, const Sched& S, const Epi& E) {
;     ...
;             PG8_LDB(B0, 1, 0); PG8_LDB(B1, 1, 1); PG8_SCHED; PG8_LDA(At, 1, 0); PG8_STAGE(PG8_SA(0, 1), a2 + hstep, voffA);
;             PG8_WAIT_V(8); PG8_WAIT_L(0); PG8_BAR; PG8_MMA(0, 0, At, B0); PG8_MMA(0, 1, At, B1); PG8_BAR; PG8_SCHED;
;             PG8_LDA(At, 1, 1); PG8_STAGE(PG8_SB(1, 0), b3, voffB); PG8_STAGE(PG8_SB(1, 1), b3 + hstep, voffB); PG8_STAGE(PG8_SA(1, 0), a3, voffA);
;             PG8_WAIT_V(8); PG8_WAIT_L(0); PG8_BAR; PG8_MMA(1, 0, At, B0); PG8_MMA(1, 1, At, B1); PG8_BAR; PG8_SCHED;
	s_add_i32 s10, 0, 0x18000
	v_add_u32_e32 v0, s10, v214
	s_add_i32 s11, 0, 0x1c000
	ds_read_b128 v[44:47], v0
	ds_read_b128 v[52:55], v0 offset:1024
	ds_read_b128 v[60:63], v0 offset:2048
	ds_read_b128 v[64:67], v0 offset:3072
	v_add_u32_e32 v0, s11, v214
	ds_read_b128 v[84:87], v0
	ds_read_b128 v[88:91], v0 offset:1024
	ds_read_b128 v[92:95], v0 offset:2048
	ds_read_b128 v[100:103], v0 offset:3072
	s_add_u32 s8, vcc_lo, 0x40000
	s_addc_u32 s9, vcc_hi, 0
	s_mov_b32 m0, s67
	v_lshl_add_u64 v[6:7], s[8:9], 0, v[176:177]
	ds_read_b128 v[128:131], v215 offset:32768
	ds_read_b128 v[132:135], v215 offset:33792
	ds_read_b128 v[140:143], v215 offset:34816
	ds_read_b128 v[188:191], v215 offset:35840
	ds_read_b128 v[192:195], v215 offset:36864
	ds_read_b128 v[196:199], v215 offset:37888
	ds_read_b128 v[216:219], v215 offset:38912
	ds_read_b128 v[220:223], v215 offset:39936
	global_load_lds_dwordx4 v[6:7], off
	v_lshl_add_u64 v[6:7], s[8:9], 0, v[180:181]
	s_mov_b32 m0, s80
	s_nop 0
	global_load_lds_dwordx4 v[6:7], off
	s_waitcnt vmcnt(8)
	s_waitcnt lgkmcnt(0)
	s_barrier
	s_waitcnt lgkmcnt(0)
	v_mfma_i32_16x16x64_i8 v[172:175], v[44:47], v[128:131], v[172:175]
	v_mfma_i32_16x16x64_i8 v[172:175], v[52:55], v[132:135], v[172:175]
	v_mfma_i32_16x16x64_i8 v[164:167], v[60:63], v[128:131], v[164:167]
	v_mfma_i32_16x16x64_i8 v[164:167], v[64:67], v[132:135], v[164:167]
	v_mfma_i32_16x16x64_i8 v[160:163], v[60:63], v[140:143], v[160:163]
	v_mfma_i32_16x16x64_i8 v[160:163], v[64:67], v[188:191], v[160:163]
	v_mfma_i32_16x16x64_i8 v[168:171], v[44:47], v[140:143], v[168:171]
	v_mfma_i32_16x16x64_i8 v[168:171], v[52:55], v[188:191], v[168:171]
	v_mfma_i32_16x16x64_i8 v[156:159], v[44:47], v[192:195], v[156:159]
	v_mfma_i32_16x16x64_i8 v[156:159], v[52:55], v[196:199], v[156:159]
	v_mfma_i32_16x16x64_i8 v[152:155], v[60:63], v[192:195], v[152:155]
	v_mfma_i32_16x16x64_i8 v[152:155], v[64:67], v[196:199], v[152:155]
	v_mfma_i32_16x16x64_i8 v[144:147], v[60:63], v[216:219], v[144:147]
	v_mfma_i32_16x16x64_i8 v[144:147], v[64:67], v[220:223], v[144:147]
	v_mfma_i32_16x16x64_i8 v[148:151], v[44:47], v[216:219], v[148:151]
	v_mfma_i32_16x16x64_i8 v[148:151], v[52:55], v[220:223], v[148:151]
	v_mfma_i32_16x16x64_i8 v[136:139], v[84:87], v[128:131], v[136:139]
	v_mfma_i32_16x16x64_i8 v[136:139], v[88:91], v[132:135], v[136:139]
	v_mfma_i32_16x16x64_i8 v[120:123], v[92:95], v[128:131], v[120:123]
	v_mfma_i32_16x16x64_i8 v[120:123], v[100:103], v[132:135], v[120:123]
	v_mfma_i32_16x16x64_i8 v[116:119], v[92:95], v[140:143], v[116:119]
	v_mfma_i32_16x16x64_i8 v[116:119], v[100:103], v[188:191], v[116:119]
	v_mfma_i32_16x16x64_i8 v[124:127], v[84:87], v[140:143], v[124:127]
	v_mfma_i32_16x16x64_i8 v[132:135], v[88:91], v[188:191], v[124:127]
	v_mfma_i32_16x16x64_i8 v[112:115], v[84:87], v[192:195], v[112:115]
	v_mfma_i32_16x16x64_i8 v[112:115], v[88:91], v[196:199], v[112:115]
	v_mfma_i32_16x16x64_i8 v[108:111], v[92:95], v[192:195], v[108:111]
	v_mfma_i32_16x16x64_i8 v[108:111], v[100:103], v[196:199], v[108:111]
	v_mfma_i32_16x16x64_i8 v[96:99], v[92:95], v[216:219], v[96:99]
	v_mfma_i32_16x16x64_i8 v[96:99], v[100:103], v[220:223], v[96:99]
	v_mfma_i32_16x16x64_i8 v[104:107], v[84:87], v[216:219], v[104:107]
	v_mfma_i32_16x16x64_i8 v[104:107], v[88:91], v[220:223], v[104:107]
	s_barrier
	s_add_i32 s8, s10, s12
	v_lshl_add_u64 v[6:7], v[200:201], 0, s[92:93]
	s_mov_b32 m0, s8
	ds_read_b128 v[124:127], v215 offset:49152
	ds_read_b128 v[128:131], v215 offset:50176
	ds_read_b128 v[140:143], v215 offset:51200
	ds_read_b128 v[188:191], v215 offset:52224
	ds_read_b128 v[192:195], v215 offset:53248
	ds_read_b128 v[196:199], v215 offset:54272
	ds_read_b128 v[216:219], v215 offset:55296
	ds_read_b128 v[220:223], v215 offset:56320
	global_load_lds_dwordx4 v[6:7], off
	s_add_i32 m0, s8, 0x2000
	s_add_u32 s8, s82, 0x40080
	v_lshl_add_u64 v[6:7], v[206:207], 0, s[92:93]
	s_addc_u32 s9, s83, 0
	s_add_i32 s10, s11, s12
	global_load_lds_dwordx4 v[6:7], off
	v_lshl_add_u64 v[6:7], s[8:9], 0, v[178:179]
	s_mov_b32 m0, s10
	s_nop 0
	global_load_lds_dwordx4 v[6:7], off
	v_lshl_add_u64 v[6:7], s[8:9], 0, v[182:183]
	s_add_i32 m0, s10, 0x2000
	s_nop 0
	global_load_lds_dwordx4 v[6:7], off
	v_lshl_add_u64 v[6:7], v[210:211], 0, s[92:93]
	s_mov_b32 m0, s58
	s_nop 0
	global_load_lds_dwordx4 v[6:7], off
	v_lshl_add_u64 v[6:7], v[224:225], 0, s[92:93]
	s_mov_b32 m0, s4
	s_nop 0
	global_load_lds_dwordx4 v[6:7], off
	s_waitcnt vmcnt(8)
	s_waitcnt lgkmcnt(0)
	s_barrier
	s_waitcnt lgkmcnt(0)
	v_mfma_i32_16x16x64_i8 v[80:83], v[44:47], v[124:127], v[80:83]
	v_mfma_i32_16x16x64_i8 v[80:83], v[52:55], v[128:131], v[80:83]
	v_mfma_i32_16x16x64_i8 v[72:75], v[60:63], v[124:127], v[72:75]
	v_mfma_i32_16x16x64_i8 v[72:75], v[64:67], v[128:131], v[72:75]
	v_mfma_i32_16x16x64_i8 v[68:71], v[60:63], v[140:143], v[68:71]
	v_mfma_i32_16x16x64_i8 v[68:71], v[64:67], v[188:191], v[68:71]
	v_mfma_i32_16x16x64_i8 v[76:79], v[44:47], v[140:143], v[76:79]
	v_mfma_i32_16x16x64_i8 v[76:79], v[52:55], v[188:191], v[76:79]
	v_mfma_i32_16x16x64_i8 v[56:59], v[44:47], v[192:195], v[56:59]
	v_mfma_i32_16x16x64_i8 v[56:59], v[52:55], v[196:199], v[56:59]
	v_mfma_i32_16x16x64_i8 v[48:51], v[60:63], v[192:195], v[48:51]
	v_mfma_i32_16x16x64_i8 v[48:51], v[64:67], v[196:199], v[48:51]
	v_mfma_i32_16x16x64_i8 v[36:39], v[60:63], v[216:219], v[36:39]
	v_mfma_i32_16x16x64_i8 v[36:39], v[64:67], v[220:223], v[36:39]
	v_mfma_i32_16x16x64_i8 v[40:43], v[44:47], v[216:219], v[40:43]
	v_mfma_i32_16x16x64_i8 v[40:43], v[52:55], v[220:223], v[40:43]
	v_mfma_i32_16x16x64_i8 v[32:35], v[84:87], v[124:127], v[32:35]
	v_mfma_i32_16x16x64_i8 v[32:35], v[88:91], v[128:131], v[32:35]
	v_mfma_i32_16x16x64_i8 v[24:27], v[92:95], v[124:127], v[24:27]
	v_mfma_i32_16x16x64_i8 v[24:27], v[100:103], v[128:131], v[24:27]
	v_mfma_i32_16x16x64_i8 v[20:23], v[92:95], v[140:143], v[20:23]
	v_mfma_i32_16x16x64_i8 v[20:23], v[100:103], v[188:191], v[20:23]
	v_mfma_i32_16x16x64_i8 v[28:31], v[84:87], v[140:143], v[28:31]
	v_mfma_i32_16x16x64_i8 v[28:31], v[88:91], v[188:191], v[28:31]
	v_mfma_i32_16x16x64_i8 v[16:19], v[84:87], v[192:195], v[16:19]
	v_mfma_i32_16x16x64_i8 v[16:19], v[88:91], v[196:199], v[16:19]
	v_mfma_i32_16x16x64_i8 v[12:15], v[92:95], v[192:195], v[12:15]
	v_mfma_i32_16x16x64_i8 v[12:15], v[100:103], v[196:199], v[12:15]
	v_mfma_i32_16x16x64_i8 v[2:5], v[92:95], v[216:219], v[2:5]
	v_mfma_i32_16x16x64_i8 v[6:9], v[84:87], v[216:219], v[8:11]
	v_mfma_i32_16x16x64_i8 v[8:11], v[88:91], v[220:223], v[6:9]
	v_mfma_i32_16x16x64_i8 v[4:7], v[100:103], v[220:223], v[2:5]
	s_barrier
	s_add_i32 s5, s5, 2
	s_add_u32 s85, s85, 0x100
	s_addc_u32 s68, s68, 0
	s_cmp_gt_u32 s5, 13
	s_mov_b64 s[8:9], s[70:71]
	s_cbranch_scc0 .LBB0_385
	s_branch .Lpeelx385
